# instruction selection pass extended: all 224 IEEE divisions (incl. SGPR-carried vcc variant) and 62 IEEE sqrt expansions in the gates epilogue replaced by v_rcp/v_sqrt; orphaned s_nop padding removed
# speedup vs baseline: 1.0142x; 1.0072x over previous
; DI u32x4 pack8(const float (&f)[8]) { u32x4 w; w.x = pk2(f[0], f[1]); w.y = pk2(f[2], f[3]); w.z = pk2(f[4], f[5]); w.w = pk2(f[6], f[7]); return w; }
; DI float silu(float x) { return x / (1.f + __expf(-x)); }
; DI void phase_gla_post(const Params& p) {
;     ...
;     for (int row = gw; row < MTOK; row += 2 * nw) {
;         u32x4 wo[2][4], wg[2][4]; bool ok[2]; size_t rr[2];
; #pragma unroll
;         for (int r = 0; r < 2; ++r) { ok[r] = row + r * nw < MTOK; rr[r] = ok[r] ? (size_t)(row + r * nw) : (size_t)row;
; #pragma unroll
;             for (int hd = 0; hd < 4; ++hd) { wo[r][hd] = *(const u32x4*)(y + rr[r] * DM + hd * 512 + lane * 8); wg[r][hd] = *(const u32x4*)(big + rr[r] * 6400 + 4096 + hd * 512 + lane * 8); } }
; #pragma unroll
;         for (int r = 0; r < 2; ++r)
; #pragma unroll
;             for (int hd = 0; hd < 4; ++hd) {
;                 float f[8], g[8]; unpack8(wo[r][hd], f); unpack8(wg[r][hd], g);
;                 float ss = 0.f;
; #pragma unroll
;                 for (int e = 0; e < 8; ++e) ss += f[e] * f[e];
;                 ss = wsum(ss); const float sc = rsqrtf(ss * (1.f / 512.f) + EPS);
; #pragma unroll
;                 for (int e = 0; e < 8; ++e) f[e] = f[e] * sc * og[e] * silu(g[e]);
;                 if (ok[r]) *(u32x4*)(y + rr[r] * DM + hd * 512 + lane * 8) = pack8(f);
;             }
.LBB0_657:
	v_ashrrev_i32_e32 v9, 31, v8
	v_lshlrev_b64 v[10:11], 12, v[8:9]
	v_lshl_add_u64 v[74:75], v[66:67], 0, v[10:11]
	v_mad_i64_i32 v[10:11], s[8:9], v8, s27, v[68:69]
	v_lshl_add_u64 v[10:11], v[10:11], 0, v[64:65]
	v_add_co_u32_e32 v12, vcc, s28, v10
	global_load_dwordx4 v[92:95], v[74:75], off
	s_nop 0
	v_addc_co_u32_e32 v13, vcc, 0, v11, vcc
	global_load_dwordx4 v[96:99], v[12:13], off
	v_add_u32_e32 v107, s62, v8
	v_cmp_gt_i32_e64 s[8:9], s3, v107
	v_lshl_add_u64 v[76:77], v[10:11], 0, s[24:25]
	s_waitcnt vmcnt(1)
	v_lshlrev_b32_e32 v80, 16, v93
	v_cndmask_b32_e64 v8, v8, v107, s[8:9]
	v_mad_i64_i32 v[12:13], s[10:11], v8, s27, v[68:69]
	v_lshl_add_u64 v[12:13], v[12:13], 0, v[64:65]
	v_add_co_u32_e32 v14, vcc, s28, v12
	v_ashrrev_i32_e32 v9, 31, v8
	s_waitcnt lgkmcnt(0)
	v_addc_co_u32_e32 v15, vcc, 0, v13, vcc
	global_load_dwordx4 v[32:35], v[14:15], off
	global_load_dwordx4 v[60:63], v[74:75], off offset:1024
	global_load_dwordx4 v[56:59], v[76:77], off offset:1024
	global_load_dwordx4 v[48:51], v[76:77], off offset:2048
	global_load_dwordx4 v[52:55], v[74:75], off offset:2048
	global_load_dwordx4 v[44:47], v[74:75], off offset:3072
	v_lshlrev_b64 v[8:9], 12, v[8:9]
	s_waitcnt vmcnt(6)
	v_lshlrev_b32_e32 v90, 16, v98
	v_and_b32_e32 v91, 0xffff0000, v98
	v_lshl_add_u64 v[72:73], v[66:67], 0, v[8:9]
	v_lshl_add_u64 v[78:79], v[12:13], 0, s[24:25]
	v_mul_f32_e32 v82, 0xbfb8aa3b, v90
	v_mul_f32_e32 v83, 0xbfb8aa3b, v91
	global_load_dwordx4 v[36:39], v[72:73], off
	global_load_dwordx4 v[28:31], v[72:73], off offset:1024
	global_load_dwordx4 v[40:43], v[76:77], off offset:3072
	global_load_dwordx4 v[24:27], v[78:79], off offset:1024
	global_load_dwordx4 v[20:23], v[72:73], off offset:2048
	global_load_dwordx4 v[12:15], v[72:73], off offset:3072
	global_load_dwordx4 v[16:19], v[78:79], off offset:2048
	global_load_dwordx4 v[8:11], v[78:79], off offset:3072
	v_lshlrev_b32_e32 v78, 16, v94
	v_and_b32_e32 v79, 0xffff0000, v94
	v_and_b32_e32 v81, 0xffff0000, v93
	v_lshlrev_b32_e32 v93, 16, v97
	v_and_b32_e32 v94, 0xffff0000, v97
	v_exp_f32_e32 v82, v82
	v_exp_f32_e32 v83, v83
	v_mul_f32_e32 v84, 0xbfb8aa3b, v93
	v_mul_f32_e32 v85, 0xbfb8aa3b, v94
	v_exp_f32_e32 v84, v84
	v_exp_f32_e32 v85, v85
	v_pk_add_f32 v[82:83], v[82:83], 1.0 op_sel_hi:[1,0]
	v_lshlrev_b32_e32 v76, 16, v95
	v_and_b32_e32 v77, 0xffff0000, v95
	v_pk_add_f32 v[84:85], v[84:85], 1.0 op_sel_hi:[1,0]
	v_rcp_f32_e32 v95, v83
	s_nop 0
	v_mul_f32_e32 v83, v91, v95
	v_rcp_f32_e32 v91, v82
	s_nop 0
	v_mul_f32_e32 v82, v90, v91
	v_rcp_f32_e32 v90, v85
	s_nop 0
	v_mul_f32_e32 v85, v94, v90
	v_lshlrev_b32_e32 v97, 16, v96
	v_and_b32_e32 v96, 0xffff0000, v96
	v_mul_f32_e32 v90, 0xbfb8aa3b, v97
	v_mul_f32_e32 v91, 0xbfb8aa3b, v96
	v_exp_f32_e32 v90, v90
	v_exp_f32_e32 v91, v91
	v_rcp_f32_e32 v98, v84
	s_nop 0
	v_mul_f32_e32 v84, v93, v98
	v_pk_add_f32 v[94:95], v[90:91], 1.0 op_sel_hi:[1,0]
	v_lshlrev_b32_e32 v90, 16, v92
	v_and_b32_e32 v91, 0xffff0000, v92
	v_lshlrev_b32_e32 v110, 16, v99
	v_and_b32_e32 v99, 0xffff0000, v99
	v_rcp_f32_e32 v92, v95
	s_nop 0
	v_mul_f32_e32 v95, v96, v92
	v_mul_f32_e32 v93, 0xbfb8aa3b, v99
	v_mul_f32_e32 v92, 0xbfb8aa3b, v110
	v_exp_f32_e32 v92, v92
	v_exp_f32_e32 v93, v93
	s_nop 0
	v_pk_add_f32 v[92:93], v[92:93], 1.0 op_sel_hi:[1,0]
	v_rcp_f32_e32 v96, v94
	s_nop 0
	v_mul_f32_e32 v94, v97, v96
	s_waitcnt vmcnt(11)
	v_lshlrev_b32_e32 v116, 16, v58
	v_rcp_f32_e32 v96, v93
	s_nop 0
	v_mul_f32_e32 v99, v99, v96
	v_and_b32_e32 v58, 0xffff0000, v58
	v_rcp_f32_e32 v93, v92
	s_nop 0
	v_mul_f32_e32 v98, v110, v93
	v_mul_f32_e32 v92, 0xbfb8aa3b, v116
	v_exp_f32_e32 v96, v92
	v_mul_f32_e32 v92, 0xbfb8aa3b, v58
	v_exp_f32_e32 v97, v92
	v_lshlrev_b32_e32 v92, 16, v63
	v_and_b32_e32 v93, 0xffff0000, v63
	v_lshlrev_b32_e32 v126, 16, v57
	v_pk_add_f32 v[110:111], v[96:97], 1.0 op_sel_hi:[1,0]
	v_lshlrev_b32_e32 v96, 16, v62
	v_and_b32_e32 v97, 0xffff0000, v62
	v_and_b32_e32 v57, 0xffff0000, v57
	v_lshlrev_b32_e32 v128, 16, v56
	v_rcp_f32_e32 v62, v111
	s_nop 0
	v_mul_f32_e32 v63, v58, v62
	v_mul_f32_e32 v111, 0xbfb8aa3b, v126
	v_exp_f32_e32 v114, v111
	v_mul_f32_e32 v111, 0xbfb8aa3b, v57
	v_exp_f32_e32 v115, v111
	v_rcp_f32_e32 v58, v110
	s_nop 0
	v_mul_f32_e32 v62, v116, v58
	v_pk_add_f32 v[114:115], v[114:115], 1.0 op_sel_hi:[1,0]
	v_lshlrev_b32_e32 v110, 16, v61
	v_and_b32_e32 v111, 0xffff0000, v61
	v_rcp_f32_e32 v58, v115
	s_nop 0
	v_mul_f32_e32 v57, v57, v58
	v_and_b32_e32 v129, 0xffff0000, v56
	v_mul_f32_e32 v56, 0xbfb8aa3b, v128
	v_exp_f32_e32 v116, v56
	v_mul_f32_e32 v56, 0xbfb8aa3b, v129
	v_exp_f32_e32 v117, v56
	v_and_b32_e32 v119, 0xffff0000, v60
	v_lshlrev_b32_e32 v118, 16, v60
	v_mov_b32_e32 v124, v119
	v_mov_b32_e32 v125, v91
	v_mov_b32_e32 v122, v118
	v_mov_b32_e32 v123, v90
	v_pk_mul_f32 v[124:125], v[124:125], v[124:125]
	v_pk_add_f32 v[60:61], v[116:117], 1.0 op_sel_hi:[1,0]
	v_mov_b32_e32 v116, v110
	v_mov_b32_e32 v117, v80
	v_pk_fma_f32 v[122:123], v[122:123], v[122:123], v[124:125]
	v_pk_mul_f32 v[88:89], v[78:79], v[78:79]
	v_pk_mul_f32 v[112:113], v[96:97], v[96:97]
	v_mov_b32_e32 v120, v111
	v_mov_b32_e32 v121, v81
	v_pk_fma_f32 v[116:117], v[116:117], v[116:117], v[122:123]
	v_pk_mul_f32 v[86:87], v[76:77], v[76:77]
	v_pk_fma_f32 v[116:117], v[120:121], v[120:121], v[116:117]
	v_mov_b32_e32 v120, v112
	v_mov_b32_e32 v121, v88
	v_pk_mul_f32 v[108:109], v[92:93], v[92:93]
	v_pk_add_f32 v[116:117], v[120:121], v[116:117]
	v_mov_b32_e32 v88, v113
	v_pk_add_f32 v[88:89], v[88:89], v[116:117]
	v_mov_b32_e32 v112, v108
	v_mov_b32_e32 v113, v86
	v_pk_add_f32 v[88:89], v[112:113], v[88:89]
	v_mov_b32_e32 v86, v109
	v_pk_add_f32 v[86:87], v[86:87], v[88:89]
	ds_bpermute_b32 v89, v100, v87
	ds_bpermute_b32 v88, v100, v86
	s_waitcnt lgkmcnt(0)
; DI u32x4 pack8(const float (&f)[8]) { u32x4 w; w.x = pk2(f[0], f[1]); w.y = pk2(f[2], f[3]); w.z = pk2(f[4], f[5]); w.w = pk2(f[6], f[7]); return w; }
; DI float silu(float x) { return x / (1.f + __expf(-x)); }
; DI void phase_gla_post(const Params& p) {
;     ...
;                 float f[8], g[8]; unpack8(wo[r][hd], f); unpack8(wg[r][hd], g);
;                 float ss = 0.f;
; #pragma unroll
;                 for (int e = 0; e < 8; ++e) ss += f[e] * f[e];
;                 ss = wsum(ss); const float sc = rsqrtf(ss * (1.f / 512.f) + EPS);
; #pragma unroll
;                 for (int e = 0; e < 8; ++e) f[e] = f[e] * sc * og[e] * silu(g[e]);
;                 if (ok[r]) *(u32x4*)(y + rr[r] * DM + hd * 512 + lane * 8) = pack8(f);
;             }
	v_pk_add_f32 v[86:87], v[86:87], v[88:89]
	ds_bpermute_b32 v89, v101, v87
	ds_bpermute_b32 v88, v101, v86
	s_waitcnt lgkmcnt(0)
	v_pk_add_f32 v[86:87], v[86:87], v[88:89]
	ds_bpermute_b32 v89, v102, v87
	ds_bpermute_b32 v88, v102, v86
	s_waitcnt lgkmcnt(0)
	v_pk_add_f32 v[86:87], v[86:87], v[88:89]
	ds_bpermute_b32 v89, v103, v87
	ds_bpermute_b32 v88, v103, v86
	v_rcp_f32_e32 v58, v61
	s_nop 0
	v_mul_f32_e32 v61, v129, v58
	s_waitcnt lgkmcnt(0)
	v_pk_add_f32 v[86:87], v[86:87], v[88:89]
	ds_bpermute_b32 v89, v104, v87
	ds_bpermute_b32 v88, v104, v86
	v_rcp_f32_e32 v56, v114
	s_nop 0
	v_mul_f32_e32 v56, v126, v56
	s_waitcnt lgkmcnt(0)
	v_pk_add_f32 v[86:87], v[86:87], v[88:89]
	ds_bpermute_b32 v89, v105, v87
	ds_bpermute_b32 v88, v105, v86
	s_waitcnt lgkmcnt(0)
	v_pk_add_f32 v[86:87], v[86:87], v[88:89]
	v_pk_fma_f32 v[86:87], v[86:87], s[26:27], v[70:71] op_sel_hi:[1,0,0]
	v_mul_f32_e32 v88, 0x4b800000, v87
	v_cmp_gt_f32_e64 s[10:11], s29, v87
	s_nop 1
	v_cndmask_b32_e64 v87, v87, v88, s[10:11]
	v_rsq_f32_e32 v87, v87
	v_rcp_f32_e32 v58, v60
	s_nop 0
	v_mul_f32_e32 v60, v128, v58
	v_cmp_gt_f32_e32 vcc, s29, v86
	v_mul_f32_e32 v58, 0x45800000, v87
	v_cndmask_b32_e64 v58, v87, v58, s[10:11]
	v_pk_mul_f32 v[88:89], v[58:59], v[90:91] op_sel_hi:[0,1]
	v_pk_mul_f32 v[80:81], v[58:59], v[80:81] op_sel_hi:[0,1]
	v_pk_mul_f32 v[78:79], v[58:59], v[78:79] op_sel_hi:[0,1]
	v_pk_mul_f32 v[76:77], v[58:59], v[76:77] op_sel_hi:[0,1]
	v_mul_f32_e32 v58, 0x4b800000, v86
	v_cndmask_b32_e32 v58, v86, v58, vcc
	v_rsq_f32_e32 v58, v58
	v_pk_mul_f32 v[88:89], v[4:5], v[88:89]
	v_pk_mul_f32 v[80:81], v[6:7], v[80:81]
	v_pk_mul_f32 v[78:79], v[0:1], v[78:79]
	v_pk_mul_f32 v[76:77], v[2:3], v[76:77]
	v_pk_mul_f32 v[88:89], v[94:95], v[88:89]
	v_pk_mul_f32 v[80:81], v[84:85], v[80:81]
	v_pk_mul_f32 v[78:79], v[82:83], v[78:79]
	v_pk_mul_f32 v[82:83], v[98:99], v[76:77]
	v_cvt_pk_bf16_f32 v76, v88, v89
	v_cvt_pk_bf16_f32 v77, v80, v81
	v_cvt_pk_bf16_f32 v78, v78, v79
	v_cvt_pk_bf16_f32 v79, v82, v83
	global_store_dwordx4 v[74:75], v[76:79], off
	v_lshlrev_b32_e32 v80, 16, v59
	s_waitcnt vmcnt(11)
	v_and_b32_e32 v84, 0xffff0000, v48
	v_mul_f32_e32 v76, 0x45800000, v58
	v_cndmask_b32_e32 v58, v58, v76, vcc
	v_pk_mul_f32 v[76:77], v[58:59], v[118:119] op_sel_hi:[0,1]
	v_pk_mul_f32 v[76:77], v[4:5], v[76:77]
	v_and_b32_e32 v59, 0xffff0000, v59
	v_pk_mul_f32 v[60:61], v[60:61], v[76:77]
	v_mul_f32_e32 v76, 0xbfb8aa3b, v80
	v_mul_f32_e32 v77, 0xbfb8aa3b, v59
	v_exp_f32_e32 v76, v76
	v_exp_f32_e32 v77, v77
	v_pk_mul_f32 v[78:79], v[58:59], v[110:111] op_sel_hi:[0,1]
	v_pk_mul_f32 v[78:79], v[6:7], v[78:79]
	s_waitcnt vmcnt(6)
	v_lshlrev_b32_e32 v110, 16, v41
	v_pk_mul_f32 v[78:79], v[56:57], v[78:79]
	v_pk_add_f32 v[56:57], v[76:77], 1.0 op_sel_hi:[1,0]
	v_pk_mul_f32 v[76:77], v[58:59], v[96:97] op_sel_hi:[0,1]
	v_pk_mul_f32 v[76:77], v[0:1], v[76:77]
	v_and_b32_e32 v41, 0xffff0000, v41
	v_pk_mul_f32 v[62:63], v[62:63], v[76:77]
	v_rcp_f32_e32 v76, v57
	s_nop 0
	v_mul_f32_e32 v57, v59, v76
	v_lshlrev_b32_e32 v112, 16, v40
	v_rcp_f32_e32 v59, v56
	s_nop 0
	v_mul_f32_e32 v56, v80, v59
	v_pk_mul_f32 v[58:59], v[58:59], v[92:93] op_sel_hi:[0,1]
	v_pk_mul_f32 v[58:59], v[2:3], v[58:59]
	v_lshlrev_b32_e32 v80, 16, v50
	v_pk_mul_f32 v[76:77], v[56:57], v[58:59]
	v_cvt_pk_bf16_f32 v56, v60, v61
	v_cvt_pk_bf16_f32 v57, v78, v79
	v_cvt_pk_bf16_f32 v58, v62, v63
	v_cvt_pk_bf16_f32 v59, v76, v77
	global_store_dwordx4 v[74:75], v[56:59], off offset:1024
	v_and_b32_e32 v50, 0xffff0000, v50
	v_lshlrev_b32_e32 v83, 16, v49
	v_mul_f32_e32 v56, 0xbfb8aa3b, v80
	v_exp_f32_e32 v58, v56
	v_mul_f32_e32 v56, 0xbfb8aa3b, v50
	v_exp_f32_e32 v59, v56
	v_lshlrev_b32_e32 v56, 16, v55
	v_and_b32_e32 v57, 0xffff0000, v55
	v_and_b32_e32 v49, 0xffff0000, v49
	v_pk_add_f32 v[60:61], v[58:59], 1.0 op_sel_hi:[1,0]
	v_lshlrev_b32_e32 v58, 16, v54
	v_and_b32_e32 v59, 0xffff0000, v54
	v_lshlrev_b32_e32 v92, 16, v42
	v_and_b32_e32 v42, 0xffff0000, v42
	v_rcp_f32_e32 v54, v61
	s_nop 0
	v_mul_f32_e32 v55, v50, v54
	v_mul_f32_e32 v61, 0xbfb8aa3b, v83
	v_exp_f32_e32 v76, v61
	v_mul_f32_e32 v61, 0xbfb8aa3b, v49
	v_exp_f32_e32 v77, v61
	v_rcp_f32_e32 v50, v60
	s_nop 0
	v_mul_f32_e32 v54, v80, v50
	v_pk_add_f32 v[76:77], v[76:77], 1.0 op_sel_hi:[1,0]
	v_lshlrev_b32_e32 v60, 16, v53
	v_and_b32_e32 v61, 0xffff0000, v53
	v_and_b32_e32 v113, 0xffff0000, v40
	v_mul_f32_e32 v40, 0xbfb8aa3b, v112
	v_rcp_f32_e32 v50, v77
	s_nop 0
	v_mul_f32_e32 v77, v49, v50
	v_lshlrev_b32_e32 v82, 16, v48
	v_mul_f32_e32 v48, 0xbfb8aa3b, v82
	v_mul_f32_e32 v49, 0xbfb8aa3b, v84
	v_exp_f32_e32 v48, v48
	v_exp_f32_e32 v49, v49
	v_rcp_f32_e32 v50, v76
	s_nop 0
	v_mul_f32_e32 v76, v83, v50
	v_pk_add_f32 v[48:49], v[48:49], 1.0 op_sel_hi:[1,0]
	v_lshlrev_b32_e32 v80, 16, v52
	v_and_b32_e32 v81, 0xffff0000, v52
	v_mov_b32_e32 v109, v81
	v_mov_b32_e32 v99, v80
	v_rcp_f32_e32 v50, v49
	s_nop 0
	v_mul_f32_e32 v53, v84, v50
	v_lshlrev_b32_e32 v84, 16, v51
	v_and_b32_e32 v85, 0xffff0000, v51
	v_mul_f32_e32 v50, 0xbfb8aa3b, v84
	v_mul_f32_e32 v51, 0xbfb8aa3b, v85
	v_exp_f32_e32 v50, v50
	v_exp_f32_e32 v51, v51
	s_nop 0
	v_pk_add_f32 v[50:51], v[50:51], 1.0 op_sel_hi:[1,0]
	v_rcp_f32_e32 v49, v48
	s_nop 0
	v_mul_f32_e32 v52, v82, v49
	v_pk_mul_f32 v[78:79], v[58:59], v[58:59]
	v_rcp_f32_e32 v48, v51
	s_nop 0
	v_mul_f32_e32 v83, v85, v48
	v_rcp_f32_e32 v48, v50
	s_nop 0
	v_mul_f32_e32 v82, v84, v48
	v_mul_f32_e32 v48, 0xbfb8aa3b, v92
	v_exp_f32_e32 v50, v48
	v_mul_f32_e32 v48, 0xbfb8aa3b, v42
	v_exp_f32_e32 v51, v48
	v_lshlrev_b32_e32 v48, 16, v47
	v_and_b32_e32 v49, 0xffff0000, v47
	v_mov_b32_e32 v97, v61
	v_pk_add_f32 v[86:87], v[50:51], 1.0 op_sel_hi:[1,0]
; DI u32x4 pack8(const float (&f)[8]) { u32x4 w; w.x = pk2(f[0], f[1]); w.y = pk2(f[2], f[3]); w.z = pk2(f[4], f[5]); w.w = pk2(f[6], f[7]); return w; }
; DI float silu(float x) { return x / (1.f + __expf(-x)); }
; DI void phase_gla_post(const Params& p) {
;     ...
;         for (int r = 0; r < 2; ++r)
; #pragma unroll
;             for (int hd = 0; hd < 4; ++hd) {
;                 float f[8], g[8]; unpack8(wo[r][hd], f); unpack8(wg[r][hd], g);
;                 float ss = 0.f;
; #pragma unroll
;                 for (int e = 0; e < 8; ++e) ss += f[e] * f[e];
;                 ss = wsum(ss); const float sc = rsqrtf(ss * (1.f / 512.f) + EPS);
; #pragma unroll
;                 for (int e = 0; e < 8; ++e) f[e] = f[e] * sc * og[e] * silu(g[e]);
;                 if (ok[r]) *(u32x4*)(y + rr[r] * DM + hd * 512 + lane * 8) = pack8(f);
	v_lshlrev_b32_e32 v50, 16, v46
	v_and_b32_e32 v51, 0xffff0000, v46
	v_pk_mul_f32 v[88:89], v[50:51], v[50:51]
	v_pk_mul_f32 v[62:63], v[56:57], v[56:57]
	v_rcp_f32_e32 v46, v87
	s_nop 0
	v_mul_f32_e32 v47, v42, v46
	v_mul_f32_e32 v87, 0xbfb8aa3b, v110
	v_exp_f32_e32 v90, v87
	v_mul_f32_e32 v87, 0xbfb8aa3b, v41
	v_exp_f32_e32 v91, v87
	v_rcp_f32_e32 v42, v86
	s_nop 0
	v_mul_f32_e32 v46, v92, v42
	v_pk_add_f32 v[90:91], v[90:91], 1.0 op_sel_hi:[1,0]
	v_lshlrev_b32_e32 v86, 16, v45
	v_and_b32_e32 v87, 0xffff0000, v45
	v_rcp_f32_e32 v42, v91
	s_nop 0
	v_mul_f32_e32 v41, v41, v42
	v_exp_f32_e32 v92, v40
	v_mul_f32_e32 v40, 0xbfb8aa3b, v113
	v_exp_f32_e32 v93, v40
	v_and_b32_e32 v95, 0xffff0000, v44
	v_lshlrev_b32_e32 v94, 16, v44
	v_mov_b32_e32 v108, v95
	v_mov_b32_e32 v98, v94
	v_pk_mul_f32 v[108:109], v[108:109], v[108:109]
	v_pk_add_f32 v[44:45], v[92:93], 1.0 op_sel_hi:[1,0]
	v_mov_b32_e32 v92, v86
	v_mov_b32_e32 v93, v60
	v_pk_fma_f32 v[98:99], v[98:99], v[98:99], v[108:109]
	v_mov_b32_e32 v96, v87
	v_pk_fma_f32 v[92:93], v[92:93], v[92:93], v[98:99]
	v_pk_mul_f32 v[84:85], v[48:49], v[48:49]
	v_pk_fma_f32 v[92:93], v[96:97], v[96:97], v[92:93]
	v_mov_b32_e32 v96, v88
	v_mov_b32_e32 v97, v78
	v_pk_add_f32 v[92:93], v[96:97], v[92:93]
	v_mov_b32_e32 v78, v89
	v_pk_add_f32 v[78:79], v[78:79], v[92:93]
	v_mov_b32_e32 v88, v84
	v_mov_b32_e32 v89, v62
	v_pk_add_f32 v[78:79], v[88:89], v[78:79]
	v_mov_b32_e32 v62, v85
	v_pk_add_f32 v[62:63], v[62:63], v[78:79]
	ds_bpermute_b32 v79, v100, v63
	ds_bpermute_b32 v78, v100, v62
	s_waitcnt lgkmcnt(0)
	v_pk_add_f32 v[62:63], v[62:63], v[78:79]
	ds_bpermute_b32 v79, v101, v63
	ds_bpermute_b32 v78, v101, v62
	s_waitcnt lgkmcnt(0)
	v_pk_add_f32 v[62:63], v[62:63], v[78:79]
	ds_bpermute_b32 v79, v102, v63
	ds_bpermute_b32 v78, v102, v62
	s_waitcnt lgkmcnt(0)
	v_pk_add_f32 v[62:63], v[62:63], v[78:79]
	ds_bpermute_b32 v79, v103, v63
	ds_bpermute_b32 v78, v103, v62
	v_rcp_f32_e32 v42, v45
	s_nop 0
	v_mul_f32_e32 v45, v113, v42
	s_waitcnt lgkmcnt(0)
	v_pk_add_f32 v[62:63], v[62:63], v[78:79]
	ds_bpermute_b32 v79, v104, v63
	ds_bpermute_b32 v78, v104, v62
	v_rcp_f32_e32 v40, v90
	s_nop 0
	v_mul_f32_e32 v40, v110, v40
	s_waitcnt lgkmcnt(0)
	v_pk_add_f32 v[62:63], v[62:63], v[78:79]
	ds_bpermute_b32 v79, v105, v63
	ds_bpermute_b32 v78, v105, v62
	s_waitcnt lgkmcnt(0)
	v_pk_add_f32 v[62:63], v[62:63], v[78:79]
	v_pk_fma_f32 v[62:63], v[62:63], s[26:27], v[70:71] op_sel_hi:[1,0,0]
	v_mul_f32_e32 v78, 0x4b800000, v63
	v_cmp_gt_f32_e64 s[10:11], s29, v63
	s_nop 1
	v_cndmask_b32_e64 v63, v63, v78, s[10:11]
	v_rsq_f32_e32 v63, v63
	v_rcp_f32_e32 v42, v44
	s_nop 0
	v_mul_f32_e32 v44, v112, v42
	v_cmp_gt_f32_e32 vcc, s29, v62
	v_mul_f32_e32 v42, 0x45800000, v63
	v_cndmask_b32_e64 v42, v63, v42, s[10:11]
	v_pk_mul_f32 v[78:79], v[42:43], v[80:81] op_sel_hi:[0,1]
	v_pk_mul_f32 v[60:61], v[42:43], v[60:61] op_sel_hi:[0,1]
	v_pk_mul_f32 v[58:59], v[42:43], v[58:59] op_sel_hi:[0,1]
	v_pk_mul_f32 v[56:57], v[42:43], v[56:57] op_sel_hi:[0,1]
	v_mul_f32_e32 v42, 0x4b800000, v62
	v_cndmask_b32_e32 v42, v62, v42, vcc
	v_rsq_f32_e32 v42, v42
	v_pk_mul_f32 v[78:79], v[4:5], v[78:79]
	v_pk_mul_f32 v[60:61], v[6:7], v[60:61]
	v_pk_mul_f32 v[58:59], v[0:1], v[58:59]
	v_pk_mul_f32 v[56:57], v[2:3], v[56:57]
	v_pk_mul_f32 v[52:53], v[52:53], v[78:79]
	v_pk_mul_f32 v[60:61], v[76:77], v[60:61]
	v_pk_mul_f32 v[54:55], v[54:55], v[58:59]
	v_pk_mul_f32 v[56:57], v[82:83], v[56:57]
	v_cvt_pk_bf16_f32 v52, v52, v53
	v_cvt_pk_bf16_f32 v53, v60, v61
	v_cvt_pk_bf16_f32 v54, v54, v55
	v_cvt_pk_bf16_f32 v55, v56, v57
	global_store_dwordx4 v[74:75], v[52:55], off offset:2048
	v_and_b32_e32 v76, 0xffff0000, v43
	s_nop 0
	v_mul_f32_e32 v52, 0x45800000, v42
	v_cndmask_b32_e32 v52, v42, v52, vcc
	v_pk_mul_f32 v[54:55], v[52:53], v[94:95] op_sel_hi:[0,1]
	v_lshlrev_b32_e32 v53, 16, v43
	v_mul_f32_e32 v42, 0xbfb8aa3b, v53
	v_mul_f32_e32 v43, 0xbfb8aa3b, v76
	v_exp_f32_e32 v42, v42
	v_exp_f32_e32 v43, v43
	v_pk_mul_f32 v[54:55], v[4:5], v[54:55]
	v_pk_add_f32 v[58:59], v[42:43], 1.0 op_sel_hi:[1,0]
	s_nop 0
	v_pk_mul_f32 v[54:55], v[44:45], v[54:55]
	v_pk_mul_f32 v[44:45], v[52:53], v[86:87] op_sel_hi:[0,1]
	v_pk_mul_f32 v[44:45], v[6:7], v[44:45]
	v_pk_mul_f32 v[56:57], v[40:41], v[44:45]
	v_pk_mul_f32 v[40:41], v[52:53], v[50:51] op_sel_hi:[0,1]
	v_pk_mul_f32 v[40:41], v[0:1], v[40:41]
	v_lshlrev_b32_e32 v44, 16, v36
	v_pk_mul_f32 v[50:51], v[46:47], v[40:41]
	v_and_b32_e32 v45, 0xffff0000, v36
	v_pk_mul_f32 v[46:47], v[44:45], v[44:45]
	v_lshlrev_b32_e32 v42, 16, v37
	v_and_b32_e32 v43, 0xffff0000, v37
	v_pk_mul_f32 v[60:61], v[42:43], v[42:43]
	v_add_f32_e32 v46, v46, v47
	v_lshlrev_b32_e32 v40, 16, v38
	v_and_b32_e32 v41, 0xffff0000, v38
	v_add_f32_e32 v46, v60, v46
	v_pk_mul_f32 v[62:63], v[40:41], v[40:41]
	v_add_f32_e32 v46, v61, v46
	v_lshlrev_b32_e32 v36, 16, v39
	v_and_b32_e32 v37, 0xffff0000, v39
	v_add_f32_e32 v46, v62, v46
	v_pk_mul_f32 v[38:39], v[36:37], v[36:37]
	v_add_f32_e32 v46, v63, v46
	v_add_f32_e32 v38, v38, v46
	v_add_f32_e32 v38, v39, v38
	ds_bpermute_b32 v39, v100, v38
	s_waitcnt lgkmcnt(0)
	v_add_f32_e32 v38, v38, v39
	ds_bpermute_b32 v61, v101, v38
	v_rcp_f32_e32 v39, v59
	s_nop 0
	v_mul_f32_e32 v39, v76, v39
	s_waitcnt lgkmcnt(0)
	v_add_f32_e32 v38, v38, v61
	ds_bpermute_b32 v46, v102, v38
	s_waitcnt lgkmcnt(0)
	v_add_f32_e32 v46, v38, v46
	ds_bpermute_b32 v62, v103, v46
	v_rcp_f32_e32 v38, v58
	s_nop 0
	v_mul_f32_e32 v38, v53, v38
	s_waitcnt lgkmcnt(0)
	v_add_f32_e32 v58, v46, v62
	ds_bpermute_b32 v59, v104, v58
	v_pk_mul_f32 v[46:47], v[52:53], v[48:49] op_sel_hi:[0,1]
	v_pk_mul_f32 v[46:47], v[2:3], v[46:47]
	v_cvt_pk_bf16_f32 v48, v50, v51
	v_pk_mul_f32 v[52:53], v[38:39], v[46:47]
	s_waitcnt lgkmcnt(0)
	v_add_f32_e32 v38, v58, v59
	ds_bpermute_b32 v39, v105, v38
	v_cvt_pk_bf16_f32 v46, v54, v55
	v_cvt_pk_bf16_f32 v47, v56, v57
	v_cvt_pk_bf16_f32 v49, v52, v53
	global_store_dwordx4 v[74:75], v[46:49], off offset:3072
	s_and_saveexec_b64 s[10:11], s[8:9]
	s_cbranch_execz .LBB0_659
; DI u32x4 pack8(const float (&f)[8]) { u32x4 w; w.x = pk2(f[0], f[1]); w.y = pk2(f[2], f[3]); w.z = pk2(f[4], f[5]); w.w = pk2(f[6], f[7]); return w; }
; DI float silu(float x) { return x / (1.f + __expf(-x)); }
; DI void phase_gla_post(const Params& p) {
;     ...
;                 float f[8], g[8]; unpack8(wo[r][hd], f); unpack8(wg[r][hd], g);
;                 float ss = 0.f;
; #pragma unroll
;                 for (int e = 0; e < 8; ++e) ss += f[e] * f[e];
;                 ss = wsum(ss); const float sc = rsqrtf(ss * (1.f / 512.f) + EPS);
; #pragma unroll
;                 for (int e = 0; e < 8; ++e) f[e] = f[e] * sc * og[e] * silu(g[e]);
;                 if (ok[r]) *(u32x4*)(y + rr[r] * DM + hd * 512 + lane * 8) = pack8(f);
	v_lshlrev_b32_e32 v48, 16, v32
	s_waitcnt lgkmcnt(0)
	v_add_f32_e32 v38, v38, v39
	v_and_b32_e32 v49, 0xffff0000, v32
	v_mul_f32_e32 v32, 0xbfb8aa3b, v48
	v_fmamk_f32 v46, v38, 0x3b000000, v106
	v_exp_f32_e32 v38, v32
	v_mul_f32_e32 v32, 0xbfb8aa3b, v49
	v_exp_f32_e32 v39, v32
	v_mul_f32_e32 v47, 0x4b800000, v46
	v_cmp_gt_f32_e32 vcc, s29, v46
	v_pk_add_f32 v[38:39], v[38:39], 1.0 op_sel_hi:[1,0]
	s_nop 0
	v_cndmask_b32_e32 v32, v46, v47, vcc
	v_rsq_f32_e32 v32, v32
	s_nop 0
	v_mul_f32_e32 v50, 0x45800000, v32
	v_cndmask_b32_e32 v32, v32, v50, vcc
	v_rcp_f32_e32 v46, v39
	s_nop 0
	v_mul_f32_e32 v39, v49, v46
	v_lshlrev_b32_e32 v51, 16, v33
	v_and_b32_e32 v33, 0xffff0000, v33
	v_mul_f32_e32 v46, 0xbfb8aa3b, v51
	v_mul_f32_e32 v47, 0xbfb8aa3b, v33
	v_exp_f32_e32 v46, v46
	v_exp_f32_e32 v47, v47
	v_rcp_f32_e32 v49, v38
	s_nop 0
	v_mul_f32_e32 v38, v48, v49
	v_pk_mul_f32 v[44:45], v[32:33], v[44:45] op_sel_hi:[0,1]
	v_pk_add_f32 v[46:47], v[46:47], 1.0 op_sel_hi:[1,0]
	v_pk_mul_f32 v[44:45], v[4:5], v[44:45]
	v_pk_mul_f32 v[38:39], v[38:39], v[44:45]
	v_lshlrev_b32_e32 v52, 16, v34
	v_and_b32_e32 v34, 0xffff0000, v34
	v_rcp_f32_e32 v44, v47
	s_nop 0
	v_mul_f32_e32 v45, v33, v44
	v_mul_f32_e32 v47, 0xbfb8aa3b, v52
	v_exp_f32_e32 v48, v47
	v_mul_f32_e32 v47, 0xbfb8aa3b, v34
	v_exp_f32_e32 v49, v47
	v_rcp_f32_e32 v33, v46
	s_nop 0
	v_mul_f32_e32 v44, v51, v33
	v_and_b32_e32 v50, 0xffff0000, v35
	v_pk_add_f32 v[46:47], v[48:49], 1.0 op_sel_hi:[1,0]
	s_nop 0
	v_pk_mul_f32 v[42:43], v[32:33], v[42:43] op_sel_hi:[0,1]
	v_pk_mul_f32 v[42:43], v[6:7], v[42:43]
	s_nop 0
	v_pk_mul_f32 v[42:43], v[44:45], v[42:43]
	v_rcp_f32_e32 v33, v47
	s_nop 0
	v_mul_f32_e32 v45, v34, v33
	v_lshlrev_b32_e32 v48, 16, v35
	v_mul_f32_e32 v34, 0xbfb8aa3b, v48
	v_mul_f32_e32 v35, 0xbfb8aa3b, v50
	v_exp_f32_e32 v34, v34
	v_exp_f32_e32 v35, v35
	v_rcp_f32_e32 v33, v46
	s_nop 0
	v_mul_f32_e32 v44, v52, v33
	v_pk_add_f32 v[34:35], v[34:35], 1.0 op_sel_hi:[1,0]
	s_nop 0
	v_pk_mul_f32 v[40:41], v[32:33], v[40:41] op_sel_hi:[0,1]
	v_pk_mul_f32 v[40:41], v[0:1], v[40:41]
	s_nop 0
	v_pk_mul_f32 v[40:41], v[44:45], v[40:41]
	v_rcp_f32_e32 v33, v35
	s_nop 0
	v_mul_f32_e32 v35, v50, v33
	v_rcp_f32_e32 v33, v34
	s_nop 0
	v_mul_f32_e32 v34, v48, v33
	v_pk_mul_f32 v[32:33], v[32:33], v[36:37] op_sel_hi:[0,1]
	v_pk_mul_f32 v[32:33], v[2:3], v[32:33]
	s_nop 0
	v_pk_mul_f32 v[36:37], v[34:35], v[32:33]
	v_cvt_pk_bf16_f32 v32, v38, v39
	v_cvt_pk_bf16_f32 v33, v42, v43
	v_cvt_pk_bf16_f32 v34, v40, v41
	v_cvt_pk_bf16_f32 v35, v36, v37
	global_store_dwordx4 v[72:73], v[32:35], off

; DI unsigned pk2(float a, float b) { f32x2 v = {a, b}; bf16v2_t r = __builtin_convertvector(v, bf16v2_t); return __builtin_bit_cast(unsigned, r); }
; DI float sigm(float x) { return 1.f / (1.f + __expf(-x)); }
;     DI void operator()(const Acc& acc, const Unit& u, int wr, int wc, int fr, int fq, const float (&pre)[8]) const {
;     ...
;         for (int n = 0; n < 2; ++n) {
;             const f32x4 br = *(const f32x4*)(brg + f0 + 4 * n), bi = *(const f32x4*)(big + f0 + 4 * n), sp = *(const f32x4*)(sp8t + f0 + 4 * n);
; #pragma unroll
;             for (int ai = 0; ai < 2; ++ai)
; #pragma unroll
;                 for (int m = 0; m < 4; ++m) { const size_t o = (size_t)(row0 + ai * HALF + m * 16) * DM + f0 + 4 * n;
;                     const u32x2 xw = *(const u32x2*)(xc + o);
;                     const float xv[4] = {__uint_as_float(xw.x << 16), __uint_as_float(xw.x & 0xffff0000u), __uint_as_float(xw.y << 16), __uint_as_float(xw.y & 0xffff0000u)};
;                     u32x4 w;
; #pragma unroll
;                     for (int e = 0; e < 4; ++e) { const float r = sigm(acc[ai][0][m][n][e] + br[e]), ig = sigm(acc[ai][1][m][n][e] + bi[e]);
;                         const float la = -sp[e] * r, uu = -2.f * la;
;                         const float om = uu * (1.f - uu * 0.5f * (1.f - uu * (1.f / 3.f) * (1.f - uu * 0.25f * (1.f - uu * 0.2f * (1.f - uu * (1.f / 6.f))))));
;                         w[e] = pk2(la, sqrtf(fmaxf(om, 0.f)) * ig * xv[e]); }
;                     *(u32x4*)(ax + o) = w; __builtin_amdgcn_sched_barrier(0); }
.LBB0_944:
	v_lshl_or_b32 v160, s84, 7, v176
	v_ashrrev_i32_e32 v161, 31, v160
	v_lshlrev_b64 v[88:89], 2, v[160:161]
	s_waitcnt lgkmcnt(0)
	v_lshl_add_u64 v[162:163], s[28:29], 0, v[88:89]
	global_load_dwordx4 v[96:99], v[162:163], off
	v_lshl_add_u64 v[164:165], s[30:31], 0, v[88:89]
	global_load_dwordx4 v[92:95], v[164:165], off
	v_lshl_add_u32 v170, s12, 8, v174
	v_ashrrev_i32_e32 v171, 31, v170
	v_lshlrev_b64 v[166:167], 11, v[170:171]
	v_lshl_add_u64 v[172:173], v[166:167], 0, v[160:161]
	v_lshl_add_u64 v[90:91], v[172:173], 1, s[16:17]
	flat_load_dwordx2 v[184:185], v[90:91]
	v_lshl_add_u64 v[168:169], s[34:35], 0, v[88:89]
	flat_load_dwordx4 v[88:91], v[168:169]
	s_waitcnt vmcnt(0)
	v_add_f32_e32 v136, v136, v96
	v_mul_f32_e32 v136, 0xbfb8aa3b, v136
	v_add_f32_e32 v133, v133, v93
	v_add_f32_e32 v132, v132, v92
	v_mul_f32_e32 v133, 0xbfb8aa3b, v133
	v_exp_f32_e32 v136, v136
	v_add_f32_e32 v137, v137, v97
	v_mul_f32_e32 v132, 0xbfb8aa3b, v132
	v_exp_f32_e32 v133, v133
	v_mul_f32_e32 v137, 0xbfb8aa3b, v137
	v_exp_f32_e32 v132, v132
	v_exp_f32_e32 v137, v137
	v_add_f32_e32 v136, 1.0, v136
	v_add_f32_e32 v190, 1.0, v133
	v_add_f32_e32 v132, 1.0, v132
	v_add_f32_e32 v137, 1.0, v137
	s_waitcnt lgkmcnt(0)
	v_lshlrev_b32_e32 v188, 16, v185
	v_and_b32_e32 v189, 0xffff0000, v185
	v_lshlrev_b32_e32 v171, 16, v184
	v_and_b32_e32 v183, 0xffff0000, v184
	v_rcp_f32_e32 v133, v136
	s_nop 0
	v_mul_f32_e64 v193, v133, -v88
	v_rcp_f32_e32 v192, v132
	v_mul_f32_e32 v132, -2.0, v193
	v_rcp_f32_e32 v136, v137
	v_mul_f32_e32 v133, 0x3e4ccccd, v132
	v_fma_f32 v157, v132, s81, 1.0
	v_mul_f32_e64 v194, v136, -v89
	v_pk_mul_f32 v[136:137], v[132:133], v[156:157]
	v_mul_f32_e32 v159, 0x3eaaaaab, v132
	v_mul_f32_e32 v184, -2.0, v194
	v_sub_f32_e32 v137, 1.0, v137
	v_mov_b32_e32 v133, v159
	v_mul_f32_e32 v186, 0x3eaaaaab, v184
	v_mul_f32_e32 v185, 0x3e4ccccd, v184
	v_fma_f32 v157, v184, s81, 1.0
	v_fma_f32 v159, -v136, v137, 1.0
	v_pk_mul_f32 v[136:137], v[184:185], v[156:157]
	v_mov_b32_e32 v185, v186
	v_pk_mul_f32 v[186:187], v[132:133], v[158:159]
	v_sub_f32_e32 v137, 1.0, v137
	v_sub_f32_e32 v133, 1.0, v187
	v_fma_f32 v133, -v186, v133, 1.0
	v_mul_f32_e32 v132, v132, v133
	v_max_f32_e32 v132, 0, v132
	v_mul_f32_e32 v133, 0x4f800000, v132
	v_cmp_gt_f32_e32 vcc, s82, v132
	v_fma_f32 v159, -v136, v137, 1.0
	v_pk_mul_f32 v[136:137], v[184:185], v[158:159]
	v_cndmask_b32_e32 v132, v132, v133, vcc
	v_sqrt_f32_e32 v133, v132
	v_add_f32_e32 v138, v138, v98
	v_mul_f32_e32 v138, 0xbfb8aa3b, v138
	v_exp_f32_e32 v138, v138
	v_add_u32_e32 v157, -1, v133
	v_add_u32_e32 v159, 1, v133
	v_fma_f32 v185, -v157, v133, v132
	v_fma_f32 v186, -v159, v133, v132
	v_cmp_ge_f32_e64 s[12:13], 0, v185
	v_add_f32_e32 v134, v134, v94
	v_mul_f32_e32 v134, 0xbfb8aa3b, v134
	v_cndmask_b32_e64 v133, v133, v157, s[12:13]
	v_cmp_lt_f32_e64 s[12:13], 0, v186
	v_exp_f32_e32 v134, v134
	v_add_f32_e32 v139, v139, v99
	v_cndmask_b32_e64 v133, v133, v159, s[12:13]
	v_mul_f32_e32 v157, 0x37800000, v133
	v_cndmask_b32_e32 v133, v133, v157, vcc
	v_cmp_class_f32_e32 vcc, v132, v182
	v_add_f32_e32 v134, 1.0, v134
	v_mul_f32_e32 v139, 0xbfb8aa3b, v139
	v_cndmask_b32_e32 v132, v133, v132, vcc
	v_sub_f32_e32 v133, 1.0, v137
	v_fma_f32 v133, -v136, v133, 1.0
	v_mul_f32_e32 v133, v184, v133
	v_max_f32_e32 v133, 0, v133
	v_rcp_f32_e32 v137, v190
	v_mul_f32_e32 v132, v192, v132
	v_mul_f32_e32 v132, v132, v171
	v_exp_f32_e32 v139, v139
	v_add_f32_e32 v135, v135, v95
	v_mul_f32_e32 v135, 0xbfb8aa3b, v135
	v_exp_f32_e32 v135, v135
	v_cvt_pk_bf16_f32 v132, v193, v132
	v_sqrt_f32_e32 v133, v133
	v_add_f32_e32 v136, 1.0, v138
	v_mul_f32_e32 v133, v137, v133
	v_mul_f32_e32 v133, v133, v183
	v_add_f32_e32 v135, 1.0, v135
	v_rcp_f32_e32 v136, v136
	s_nop 0
	v_mul_f32_e64 v186, v136, -v90
	v_mul_f32_e32 v136, -2.0, v186
	v_mul_f32_e32 v137, 0x3e4ccccd, v136
	v_fma_f32 v157, v136, s81, 1.0
	v_pk_mul_f32 v[184:185], v[136:137], v[156:157]
	v_mul_f32_e32 v187, 0x3eaaaaab, v136
	v_sub_f32_e32 v137, 1.0, v185
	v_fma_f32 v159, -v184, v137, 1.0
	v_mov_b32_e32 v137, v187
	v_pk_mul_f32 v[184:185], v[136:137], v[158:159]
	v_sub_f32_e32 v137, 1.0, v185
	v_fma_f32 v137, -v184, v137, 1.0
	v_mul_f32_e32 v136, v136, v137
	v_max_f32_e32 v136, 0, v136
	v_rcp_f32_e32 v134, v134
	v_cvt_pk_bf16_f32 v133, v194, v133
	v_sqrt_f32_e32 v136, v136
	v_add_f32_e32 v137, 1.0, v139
	v_mul_f32_e32 v134, v134, v136
	v_mul_f32_e32 v134, v134, v188
	v_cvt_pk_bf16_f32 v134, v186, v134
	v_rcp_f32_e32 v136, v137
	s_nop 0
	v_mul_f32_e64 v185, v136, -v91
	v_mul_f32_e32 v136, -2.0, v185
	v_mul_f32_e32 v137, 0x3e4ccccd, v136
	v_fma_f32 v157, v136, s81, 1.0
	v_pk_mul_f32 v[138:139], v[136:137], v[156:157]
	v_mul_f32_e32 v186, 0x3eaaaaab, v136
	v_sub_f32_e32 v137, 1.0, v139
	v_fma_f32 v159, -v138, v137, 1.0
	v_mov_b32_e32 v137, v186
	v_pk_mul_f32 v[138:139], v[136:137], v[158:159]
	s_nop 0
	v_sub_f32_e32 v137, 1.0, v139
	v_fma_f32 v137, -v138, v137, 1.0
	v_mul_f32_e32 v136, v136, v137
	v_max_f32_e32 v136, 0, v136
	v_rcp_f32_e32 v135, v135
	v_sqrt_f32_e32 v136, v136
	s_nop 0
	v_mul_f32_e32 v135, v135, v136
	v_mul_f32_e32 v135, v135, v189
	v_cvt_pk_bf16_f32 v135, v185, v135
	v_lshl_add_u64 v[136:137], v[172:173], 2, s[36:37]
	flat_store_dwordx4 v[136:137], v[132:135]
	s_nop 1
	v_or_b32_e32 v132, 16, v170
	v_ashrrev_i32_e32 v133, 31, v132
	v_lshlrev_b64 v[132:133], 11, v[132:133]
	v_lshl_add_u64 v[134:135], v[132:133], 0, v[160:161]
	v_lshl_add_u64 v[136:137], v[134:135], 1, s[16:17]
	flat_load_dwordx2 v[136:137], v[136:137]
	v_add_f32_e32 v128, v128, v96
	v_add_f32_e32 v129, v129, v97
	v_mul_f32_e32 v128, 0xbfb8aa3b, v128
	v_mul_f32_e32 v129, 0xbfb8aa3b, v129
	v_exp_f32_e32 v128, v128
	v_exp_f32_e32 v129, v129
	v_add_f32_e32 v124, v124, v92
	v_mul_f32_e32 v124, 0xbfb8aa3b, v124
	v_add_f32_e32 v128, 1.0, v128
	v_add_f32_e32 v171, 1.0, v129
	v_exp_f32_e32 v124, v124
	s_nop 0
	v_add_f32_e32 v124, 1.0, v124
	v_rcp_f32_e32 v128, v128
	s_nop 0
	v_mul_f32_e64 v184, v128, -v88
	v_mul_f32_e32 v128, -2.0, v184
	v_mul_f32_e32 v129, 0x3e4ccccd, v128
	v_fma_f32 v157, v128, s81, 1.0
	v_pk_mul_f32 v[138:139], v[128:129], v[156:157]
	v_mul_f32_e32 v159, 0x3eaaaaab, v128
	v_sub_f32_e32 v139, 1.0, v139
	v_mov_b32_e32 v129, v159
	v_fma_f32 v159, -v138, v139, 1.0
	v_pk_mul_f32 v[138:139], v[128:129], v[158:159]
	v_sub_f32_e32 v129, 1.0, v139
	v_fma_f32 v129, -v138, v129, 1.0
	v_mul_f32_e32 v128, v128, v129
	v_max_f32_e32 v128, 0, v128
	v_rcp_f32_e32 v124, v124
	v_add_f32_e32 v125, v125, v93
	v_mul_f32_e32 v125, 0xbfb8aa3b, v125
	v_exp_f32_e32 v125, v125
	s_nop 0
	v_add_f32_e32 v125, 1.0, v125
	v_add_f32_e32 v130, v130, v98
	v_mul_f32_e32 v130, 0xbfb8aa3b, v130
	v_exp_f32_e32 v130, v130
	s_waitcnt vmcnt(0) lgkmcnt(0)
; DI unsigned pk2(float a, float b) { f32x2 v = {a, b}; bf16v2_t r = __builtin_convertvector(v, bf16v2_t); return __builtin_bit_cast(unsigned, r); }
; DI float sigm(float x) { return 1.f / (1.f + __expf(-x)); }
;     DI void operator()(const Acc& acc, const Unit& u, int wr, int wc, int fr, int fq, const float (&pre)[8]) const {
;     ...
;         for (int n = 0; n < 2; ++n) {
;             const f32x4 br = *(const f32x4*)(brg + f0 + 4 * n), bi = *(const f32x4*)(big + f0 + 4 * n), sp = *(const f32x4*)(sp8t + f0 + 4 * n);
; #pragma unroll
;             for (int ai = 0; ai < 2; ++ai)
; #pragma unroll
;                 for (int m = 0; m < 4; ++m) { const size_t o = (size_t)(row0 + ai * HALF + m * 16) * DM + f0 + 4 * n;
;                     const u32x2 xw = *(const u32x2*)(xc + o);
;                     const float xv[4] = {__uint_as_float(xw.x << 16), __uint_as_float(xw.x & 0xffff0000u), __uint_as_float(xw.y << 16), __uint_as_float(xw.y & 0xffff0000u)};
;                     u32x4 w;
; #pragma unroll
;                     for (int e = 0; e < 4; ++e) { const float r = sigm(acc[ai][0][m][n][e] + br[e]), ig = sigm(acc[ai][1][m][n][e] + bi[e]);
;                         const float la = -sp[e] * r, uu = -2.f * la;
;                         const float om = uu * (1.f - uu * 0.5f * (1.f - uu * (1.f / 3.f) * (1.f - uu * 0.25f * (1.f - uu * 0.2f * (1.f - uu * (1.f / 6.f))))));
;                         w[e] = pk2(la, sqrtf(fmaxf(om, 0.f)) * ig * xv[e]); }
;                     *(u32x4*)(ax + o) = w; __builtin_amdgcn_sched_barrier(0); }
	v_and_b32_e32 v138, 0xffff0000, v136
	v_lshlrev_b32_e32 v139, 16, v137
	v_sqrt_f32_e32 v128, v128
	s_nop 0
	v_mul_f32_e32 v124, v124, v128
	v_lshlrev_b32_e32 v128, 16, v136
	v_mul_f32_e32 v124, v124, v128
	v_rcp_f32_e32 v128, v171
	v_and_b32_e32 v173, 0xffff0000, v137
	v_cvt_pk_bf16_f32 v124, v184, v124
	v_mul_f32_e64 v184, v128, -v89
	v_mul_f32_e32 v128, -2.0, v184
	v_mul_f32_e32 v129, 0x3e4ccccd, v128
	v_fma_f32 v157, v128, s81, 1.0
	v_pk_mul_f32 v[136:137], v[128:129], v[156:157]
	v_mul_f32_e32 v185, 0x3eaaaaab, v128
	v_sub_f32_e32 v129, 1.0, v137
	v_fma_f32 v159, -v136, v129, 1.0
	v_mov_b32_e32 v129, v185
	v_pk_mul_f32 v[136:137], v[128:129], v[158:159]
	v_add_f32_e32 v126, v126, v94
	v_sub_f32_e32 v129, 1.0, v137
	v_fma_f32 v129, -v136, v129, 1.0
	v_mul_f32_e32 v128, v128, v129
	v_max_f32_e32 v128, 0, v128
	v_rcp_f32_e32 v125, v125
	v_mul_f32_e32 v126, 0xbfb8aa3b, v126
	v_exp_f32_e32 v126, v126
	v_add_f32_e32 v131, v131, v99
	v_add_f32_e32 v126, 1.0, v126
	v_mul_f32_e32 v131, 0xbfb8aa3b, v131
	v_exp_f32_e32 v131, v131
	v_add_f32_e32 v127, v127, v95
	v_mul_f32_e32 v127, 0xbfb8aa3b, v127
	v_sqrt_f32_e32 v128, v128
	v_add_f32_e32 v129, 1.0, v130
	v_mul_f32_e32 v125, v125, v128
	v_mul_f32_e32 v125, v125, v138
	v_exp_f32_e32 v127, v127
	v_rcp_f32_e32 v128, v129
	s_nop 0
	v_mul_f32_e64 v172, v128, -v90
	v_mul_f32_e32 v128, -2.0, v172
	v_mul_f32_e32 v129, 0x3e4ccccd, v128
	v_fma_f32 v157, v128, s81, 1.0
	v_pk_mul_f32 v[136:137], v[128:129], v[156:157]
	v_mul_f32_e32 v183, 0x3eaaaaab, v128
	v_sub_f32_e32 v129, 1.0, v137
	v_fma_f32 v159, -v136, v129, 1.0
	v_mov_b32_e32 v129, v183
	v_pk_mul_f32 v[136:137], v[128:129], v[158:159]
	v_sub_f32_e32 v129, 1.0, v137
	v_fma_f32 v129, -v136, v129, 1.0
	v_mul_f32_e32 v128, v128, v129
	v_max_f32_e32 v128, 0, v128
	v_rcp_f32_e32 v126, v126
	v_add_f32_e32 v127, 1.0, v127
	v_cvt_pk_bf16_f32 v125, v184, v125
	v_sqrt_f32_e32 v128, v128
	v_add_f32_e32 v129, 1.0, v131
	v_mul_f32_e32 v126, v126, v128
	v_mul_f32_e32 v126, v126, v139
	v_cvt_pk_bf16_f32 v126, v172, v126
	v_rcp_f32_e32 v128, v129
	s_nop 0
	v_mul_f32_e64 v139, v128, -v91
	v_mul_f32_e32 v128, -2.0, v139
	v_mul_f32_e32 v129, 0x3e4ccccd, v128
	v_fma_f32 v157, v128, s81, 1.0
	v_pk_mul_f32 v[130:131], v[128:129], v[156:157]
	v_mul_f32_e32 v171, 0x3eaaaaab, v128
	v_sub_f32_e32 v129, 1.0, v131
	v_fma_f32 v159, -v130, v129, 1.0
	v_mov_b32_e32 v129, v171
	v_pk_mul_f32 v[130:131], v[128:129], v[158:159]
	s_nop 0
	v_sub_f32_e32 v129, 1.0, v131
	v_fma_f32 v129, -v130, v129, 1.0
	v_mul_f32_e32 v128, v128, v129
	v_max_f32_e32 v128, 0, v128
	v_rcp_f32_e32 v127, v127
	v_sqrt_f32_e32 v128, v128
	s_nop 0
	v_mul_f32_e32 v127, v127, v128
	v_mul_f32_e32 v127, v127, v173
	v_cvt_pk_bf16_f32 v127, v139, v127
	v_lshl_add_u64 v[128:129], v[134:135], 2, s[36:37]
	flat_store_dwordx4 v[128:129], v[124:127]
	s_nop 1
	v_or_b32_e32 v124, 32, v170
	v_ashrrev_i32_e32 v125, 31, v124
	v_lshlrev_b64 v[124:125], 11, v[124:125]
	v_lshl_add_u64 v[126:127], v[124:125], 0, v[160:161]
	v_lshl_add_u64 v[128:129], v[126:127], 1, s[16:17]
	flat_load_dwordx2 v[128:129], v[128:129]
	v_add_f32_e32 v120, v120, v96
	v_add_f32_e32 v121, v121, v97
	v_mul_f32_e32 v120, 0xbfb8aa3b, v120
	v_add_f32_e32 v116, v116, v92
	v_mul_f32_e32 v121, 0xbfb8aa3b, v121
	v_exp_f32_e32 v120, v120
	v_mul_f32_e32 v116, 0xbfb8aa3b, v116
	v_exp_f32_e32 v121, v121
	v_exp_f32_e32 v116, v116
	v_add_f32_e32 v120, 1.0, v120
	v_add_f32_e32 v134, 1.0, v121
	v_add_f32_e32 v116, 1.0, v116
	v_rcp_f32_e32 v120, v120
	s_nop 0
	v_mul_f32_e64 v136, v120, -v88
	v_mul_f32_e32 v120, -2.0, v136
	v_mul_f32_e32 v121, 0x3e4ccccd, v120
	v_fma_f32 v157, v120, s81, 1.0
	v_pk_mul_f32 v[130:131], v[120:121], v[156:157]
	v_mul_f32_e32 v159, 0x3eaaaaab, v120
	v_sub_f32_e32 v131, 1.0, v131
	v_mov_b32_e32 v121, v159
	v_fma_f32 v159, -v130, v131, 1.0
	v_pk_mul_f32 v[130:131], v[120:121], v[158:159]
	v_sub_f32_e32 v121, 1.0, v131
	v_fma_f32 v121, -v130, v121, 1.0
	v_mul_f32_e32 v120, v120, v121
	v_max_f32_e32 v120, 0, v120
	v_rcp_f32_e32 v116, v116
	v_add_f32_e32 v117, v117, v93
	v_mul_f32_e32 v117, 0xbfb8aa3b, v117
	v_exp_f32_e32 v117, v117
	s_nop 0
	v_add_f32_e32 v117, 1.0, v117
	v_add_f32_e32 v122, v122, v98
	v_mul_f32_e32 v122, 0xbfb8aa3b, v122
	v_exp_f32_e32 v122, v122
	s_waitcnt vmcnt(0) lgkmcnt(0)
; DI unsigned pk2(float a, float b) { f32x2 v = {a, b}; bf16v2_t r = __builtin_convertvector(v, bf16v2_t); return __builtin_bit_cast(unsigned, r); }
; DI float sigm(float x) { return 1.f / (1.f + __expf(-x)); }
;     DI void operator()(const Acc& acc, const Unit& u, int wr, int wc, int fr, int fq, const float (&pre)[8]) const {
;     ...
;         for (int n = 0; n < 2; ++n) {
;             const f32x4 br = *(const f32x4*)(brg + f0 + 4 * n), bi = *(const f32x4*)(big + f0 + 4 * n), sp = *(const f32x4*)(sp8t + f0 + 4 * n);
; #pragma unroll
;             for (int ai = 0; ai < 2; ++ai)
; #pragma unroll
;                 for (int m = 0; m < 4; ++m) { const size_t o = (size_t)(row0 + ai * HALF + m * 16) * DM + f0 + 4 * n;
;                     const u32x2 xw = *(const u32x2*)(xc + o);
;                     const float xv[4] = {__uint_as_float(xw.x << 16), __uint_as_float(xw.x & 0xffff0000u), __uint_as_float(xw.y << 16), __uint_as_float(xw.y & 0xffff0000u)};
;                     u32x4 w;
; #pragma unroll
;                     for (int e = 0; e < 4; ++e) { const float r = sigm(acc[ai][0][m][n][e] + br[e]), ig = sigm(acc[ai][1][m][n][e] + bi[e]);
;                         const float la = -sp[e] * r, uu = -2.f * la;
;                         const float om = uu * (1.f - uu * 0.5f * (1.f - uu * (1.f / 3.f) * (1.f - uu * 0.25f * (1.f - uu * 0.2f * (1.f - uu * (1.f / 6.f))))));
;                         w[e] = pk2(la, sqrtf(fmaxf(om, 0.f)) * ig * xv[e]); }
;                     *(u32x4*)(ax + o) = w; __builtin_amdgcn_sched_barrier(0); }
	v_and_b32_e32 v130, 0xffff0000, v128
	v_lshlrev_b32_e32 v131, 16, v129
	v_sqrt_f32_e32 v120, v120
	s_nop 0
	v_mul_f32_e32 v116, v116, v120
	v_lshlrev_b32_e32 v120, 16, v128
	v_mul_f32_e32 v116, v116, v120
	v_rcp_f32_e32 v120, v134
	v_and_b32_e32 v137, 0xffff0000, v129
	v_mul_f32_e64 v138, v120, -v89
	v_mul_f32_e32 v120, -2.0, v138
	v_cvt_pk_bf16_f32 v116, v136, v116
	v_mul_f32_e32 v121, 0x3e4ccccd, v120
	v_fma_f32 v157, v120, s81, 1.0
	v_pk_mul_f32 v[128:129], v[120:121], v[156:157]
	v_mul_f32_e32 v139, 0x3eaaaaab, v120
	v_sub_f32_e32 v121, 1.0, v129
	v_fma_f32 v159, -v128, v121, 1.0
	v_mov_b32_e32 v121, v139
	v_pk_mul_f32 v[128:129], v[120:121], v[158:159]
	v_add_f32_e32 v118, v118, v94
	v_sub_f32_e32 v121, 1.0, v129
	v_fma_f32 v121, -v128, v121, 1.0
	v_mul_f32_e32 v120, v120, v121
	v_max_f32_e32 v120, 0, v120
	v_rcp_f32_e32 v117, v117
	v_mul_f32_e32 v118, 0xbfb8aa3b, v118
	v_exp_f32_e32 v118, v118
	v_add_f32_e32 v123, v123, v99
	v_add_f32_e32 v118, 1.0, v118
	v_mul_f32_e32 v123, 0xbfb8aa3b, v123
	v_exp_f32_e32 v123, v123
	v_add_f32_e32 v119, v119, v95
	v_mul_f32_e32 v119, 0xbfb8aa3b, v119
	v_sqrt_f32_e32 v120, v120
	v_add_f32_e32 v121, 1.0, v122
	v_mul_f32_e32 v117, v117, v120
	v_mul_f32_e32 v117, v117, v130
	v_exp_f32_e32 v119, v119
	v_rcp_f32_e32 v120, v121
	s_nop 0
	v_mul_f32_e64 v135, v120, -v90
	v_mul_f32_e32 v120, -2.0, v135
	v_mul_f32_e32 v121, 0x3e4ccccd, v120
	v_fma_f32 v157, v120, s81, 1.0
	v_pk_mul_f32 v[128:129], v[120:121], v[156:157]
	v_mul_f32_e32 v136, 0x3eaaaaab, v120
	v_sub_f32_e32 v121, 1.0, v129
	v_fma_f32 v159, -v128, v121, 1.0
	v_mov_b32_e32 v121, v136
	v_pk_mul_f32 v[128:129], v[120:121], v[158:159]
	v_sub_f32_e32 v121, 1.0, v129
	v_fma_f32 v121, -v128, v121, 1.0
	v_mul_f32_e32 v120, v120, v121
	v_max_f32_e32 v120, 0, v120
	v_rcp_f32_e32 v118, v118
	v_add_f32_e32 v119, 1.0, v119
	v_cvt_pk_bf16_f32 v117, v138, v117
	v_sqrt_f32_e32 v120, v120
	v_add_f32_e32 v121, 1.0, v123
	v_mul_f32_e32 v118, v118, v120
	v_mul_f32_e32 v118, v118, v131
	v_cvt_pk_bf16_f32 v118, v135, v118
	v_rcp_f32_e32 v120, v121
	s_nop 0
	v_mul_f32_e64 v131, v120, -v91
	v_mul_f32_e32 v120, -2.0, v131
	v_mul_f32_e32 v121, 0x3e4ccccd, v120
	v_fma_f32 v157, v120, s81, 1.0
	v_pk_mul_f32 v[122:123], v[120:121], v[156:157]
	v_mul_f32_e32 v134, 0x3eaaaaab, v120
	v_sub_f32_e32 v121, 1.0, v123
	v_fma_f32 v159, -v122, v121, 1.0
	v_mov_b32_e32 v121, v134
	v_pk_mul_f32 v[122:123], v[120:121], v[158:159]
	s_nop 0
	v_sub_f32_e32 v121, 1.0, v123
	v_fma_f32 v121, -v122, v121, 1.0
	v_mul_f32_e32 v120, v120, v121
	v_max_f32_e32 v120, 0, v120
	v_rcp_f32_e32 v119, v119
	v_sqrt_f32_e32 v120, v120
	s_nop 0
	v_mul_f32_e32 v119, v119, v120
	v_mul_f32_e32 v119, v119, v137
	v_cvt_pk_bf16_f32 v119, v131, v119
	v_lshl_add_u64 v[120:121], v[126:127], 2, s[36:37]
	flat_store_dwordx4 v[120:121], v[116:119]
	s_nop 1
	v_or_b32_e32 v116, 48, v170
	v_ashrrev_i32_e32 v117, 31, v116
	v_lshlrev_b64 v[116:117], 11, v[116:117]
	v_lshl_add_u64 v[118:119], v[116:117], 0, v[160:161]
	v_lshl_add_u64 v[120:121], v[118:119], 1, s[16:17]
	flat_load_dwordx2 v[120:121], v[120:121]
	v_add_f32_e32 v112, v112, v96
	v_add_f32_e32 v113, v113, v97
	v_mul_f32_e32 v112, 0xbfb8aa3b, v112
	v_mul_f32_e32 v113, 0xbfb8aa3b, v113
	v_exp_f32_e32 v112, v112
	v_exp_f32_e32 v113, v113
	v_add_f32_e32 v108, v108, v92
	v_mul_f32_e32 v108, 0xbfb8aa3b, v108
	v_add_f32_e32 v112, 1.0, v112
	v_add_f32_e32 v126, 1.0, v113
	v_exp_f32_e32 v108, v108
	s_nop 0
	v_add_f32_e32 v108, 1.0, v108
	v_rcp_f32_e32 v112, v112
	s_nop 0
	v_mul_f32_e64 v128, v112, -v88
	v_mul_f32_e32 v112, -2.0, v128
	v_mul_f32_e32 v113, 0x3e4ccccd, v112
	v_fma_f32 v157, v112, s81, 1.0
	v_pk_mul_f32 v[122:123], v[112:113], v[156:157]
	v_mul_f32_e32 v134, 0x3eaaaaab, v112
	v_sub_f32_e32 v123, 1.0, v123
	v_mov_b32_e32 v113, v134
	v_fma_f32 v159, -v122, v123, 1.0
	v_pk_mul_f32 v[122:123], v[112:113], v[158:159]
	v_sub_f32_e32 v113, 1.0, v123
	v_fma_f32 v113, -v122, v113, 1.0
	v_mul_f32_e32 v112, v112, v113
	v_max_f32_e32 v112, 0, v112
	v_rcp_f32_e32 v108, v108
	v_add_f32_e32 v109, v109, v93
	v_mul_f32_e32 v109, 0xbfb8aa3b, v109
	v_exp_f32_e32 v109, v109
	s_nop 0
	v_add_f32_e32 v109, 1.0, v109
	v_add_f32_e32 v114, v114, v98
	v_mul_f32_e32 v114, 0xbfb8aa3b, v114
	v_exp_f32_e32 v114, v114
	s_waitcnt vmcnt(0) lgkmcnt(0)
; DI unsigned pk2(float a, float b) { f32x2 v = {a, b}; bf16v2_t r = __builtin_convertvector(v, bf16v2_t); return __builtin_bit_cast(unsigned, r); }
; DI float sigm(float x) { return 1.f / (1.f + __expf(-x)); }
;     DI void operator()(const Acc& acc, const Unit& u, int wr, int wc, int fr, int fq, const float (&pre)[8]) const {
;     ...
;         for (int n = 0; n < 2; ++n) {
;             const f32x4 br = *(const f32x4*)(brg + f0 + 4 * n), bi = *(const f32x4*)(big + f0 + 4 * n), sp = *(const f32x4*)(sp8t + f0 + 4 * n);
; #pragma unroll
;             for (int ai = 0; ai < 2; ++ai)
; #pragma unroll
;                 for (int m = 0; m < 4; ++m) { const size_t o = (size_t)(row0 + ai * HALF + m * 16) * DM + f0 + 4 * n;
;                     const u32x2 xw = *(const u32x2*)(xc + o);
;                     const float xv[4] = {__uint_as_float(xw.x << 16), __uint_as_float(xw.x & 0xffff0000u), __uint_as_float(xw.y << 16), __uint_as_float(xw.y & 0xffff0000u)};
;                     u32x4 w;
; #pragma unroll
;                     for (int e = 0; e < 4; ++e) { const float r = sigm(acc[ai][0][m][n][e] + br[e]), ig = sigm(acc[ai][1][m][n][e] + bi[e]);
;                         const float la = -sp[e] * r, uu = -2.f * la;
;                         const float om = uu * (1.f - uu * 0.5f * (1.f - uu * (1.f / 3.f) * (1.f - uu * 0.25f * (1.f - uu * 0.2f * (1.f - uu * (1.f / 6.f))))));
;                         w[e] = pk2(la, sqrtf(fmaxf(om, 0.f)) * ig * xv[e]); }
;                     *(u32x4*)(ax + o) = w; __builtin_amdgcn_sched_barrier(0); }
	v_and_b32_e32 v122, 0xffff0000, v120
	v_lshlrev_b32_e32 v123, 16, v121
	v_sqrt_f32_e32 v112, v112
	s_nop 0
	v_mul_f32_e32 v108, v108, v112
	v_lshlrev_b32_e32 v112, 16, v120
	v_mul_f32_e32 v108, v108, v112
	v_rcp_f32_e32 v112, v126
	v_and_b32_e32 v129, 0xffff0000, v121
	v_mul_f32_e64 v130, v112, -v89
	v_mul_f32_e32 v112, -2.0, v130
	v_cvt_pk_bf16_f32 v108, v128, v108
	v_mul_f32_e32 v113, 0x3e4ccccd, v112
	v_fma_f32 v157, v112, s81, 1.0
	v_pk_mul_f32 v[120:121], v[112:113], v[156:157]
	v_mul_f32_e32 v131, 0x3eaaaaab, v112
	v_sub_f32_e32 v113, 1.0, v121
	v_fma_f32 v159, -v120, v113, 1.0
	v_mov_b32_e32 v113, v131
	v_pk_mul_f32 v[120:121], v[112:113], v[158:159]
	v_add_f32_e32 v110, v110, v94
	v_sub_f32_e32 v113, 1.0, v121
	v_fma_f32 v113, -v120, v113, 1.0
	v_mul_f32_e32 v112, v112, v113
	v_max_f32_e32 v112, 0, v112
	v_rcp_f32_e32 v109, v109
	v_mul_f32_e32 v110, 0xbfb8aa3b, v110
	v_exp_f32_e32 v110, v110
	v_add_f32_e32 v115, v115, v99
	v_add_f32_e32 v110, 1.0, v110
	v_mul_f32_e32 v115, 0xbfb8aa3b, v115
	v_exp_f32_e32 v115, v115
	v_add_f32_e32 v111, v111, v95
	v_mul_f32_e32 v111, 0xbfb8aa3b, v111
	v_sqrt_f32_e32 v112, v112
	v_add_f32_e32 v113, 1.0, v114
	v_mul_f32_e32 v109, v109, v112
	v_mul_f32_e32 v109, v109, v122
	v_exp_f32_e32 v111, v111
	v_rcp_f32_e32 v112, v113
	s_nop 0
	v_mul_f32_e64 v127, v112, -v90
	v_mul_f32_e32 v112, -2.0, v127
	v_mul_f32_e32 v113, 0x3e4ccccd, v112
	v_fma_f32 v157, v112, s81, 1.0
	v_pk_mul_f32 v[120:121], v[112:113], v[156:157]
	v_mul_f32_e32 v128, 0x3eaaaaab, v112
	v_sub_f32_e32 v113, 1.0, v121
	v_fma_f32 v159, -v120, v113, 1.0
	v_mov_b32_e32 v113, v128
	v_pk_mul_f32 v[120:121], v[112:113], v[158:159]
	v_sub_f32_e32 v113, 1.0, v121
	v_fma_f32 v113, -v120, v113, 1.0
	v_mul_f32_e32 v112, v112, v113
	v_max_f32_e32 v112, 0, v112
	v_rcp_f32_e32 v110, v110
	v_add_f32_e32 v111, 1.0, v111
	v_cvt_pk_bf16_f32 v109, v130, v109
	v_sqrt_f32_e32 v112, v112
	v_add_f32_e32 v113, 1.0, v115
	v_mul_f32_e32 v110, v110, v112
	v_mul_f32_e32 v110, v110, v123
	v_cvt_pk_bf16_f32 v110, v127, v110
	v_rcp_f32_e32 v112, v113
	s_nop 0
	v_mul_f32_e64 v123, v112, -v91
	v_mul_f32_e32 v112, -2.0, v123
	v_mul_f32_e32 v113, 0x3e4ccccd, v112
	v_fma_f32 v157, v112, s81, 1.0
	v_pk_mul_f32 v[114:115], v[112:113], v[156:157]
	v_mul_f32_e32 v126, 0x3eaaaaab, v112
	v_sub_f32_e32 v113, 1.0, v115
	v_fma_f32 v159, -v114, v113, 1.0
	v_mov_b32_e32 v113, v126
	v_pk_mul_f32 v[114:115], v[112:113], v[158:159]
	s_nop 0
	v_sub_f32_e32 v113, 1.0, v115
	v_fma_f32 v113, -v114, v113, 1.0
	v_mul_f32_e32 v112, v112, v113
	v_max_f32_e32 v112, 0, v112
	v_rcp_f32_e32 v111, v111
	v_sqrt_f32_e32 v112, v112
	s_nop 0
	v_mul_f32_e32 v111, v111, v112
	v_mul_f32_e32 v111, v111, v129
	v_cvt_pk_bf16_f32 v111, v123, v111
	v_lshl_add_u64 v[112:113], v[118:119], 2, s[36:37]
	flat_store_dwordx4 v[112:113], v[108:111]
	s_nop 1
	v_lshl_add_u64 v[108:109], v[166:167], 0, s[42:43]
	v_lshl_add_u64 v[110:111], v[108:109], 0, v[160:161]
	v_lshl_add_u64 v[112:113], v[110:111], 1, s[16:17]
	flat_load_dwordx2 v[112:113], v[112:113]
	v_add_f32_e32 v104, v104, v96
	v_add_f32_e32 v105, v105, v97
	v_mul_f32_e32 v104, 0xbfb8aa3b, v104
	v_mul_f32_e32 v105, 0xbfb8aa3b, v105
	v_exp_f32_e32 v104, v104
	v_exp_f32_e32 v105, v105
	v_add_f32_e32 v100, v100, v92
	v_mul_f32_e32 v100, 0xbfb8aa3b, v100
	v_add_f32_e32 v104, 1.0, v104
	v_add_f32_e32 v118, 1.0, v105
	v_exp_f32_e32 v100, v100
	s_nop 0
	v_add_f32_e32 v100, 1.0, v100
	v_rcp_f32_e32 v104, v104
	s_nop 0
	v_mul_f32_e64 v120, v104, -v88
	v_mul_f32_e32 v104, -2.0, v120
	v_mul_f32_e32 v105, 0x3e4ccccd, v104
	v_fma_f32 v157, v104, s81, 1.0
	v_pk_mul_f32 v[114:115], v[104:105], v[156:157]
	v_mul_f32_e32 v126, 0x3eaaaaab, v104
	v_sub_f32_e32 v115, 1.0, v115
	v_mov_b32_e32 v105, v126
	v_fma_f32 v159, -v114, v115, 1.0
	v_pk_mul_f32 v[114:115], v[104:105], v[158:159]
	v_sub_f32_e32 v105, 1.0, v115
	v_fma_f32 v105, -v114, v105, 1.0
	v_mul_f32_e32 v104, v104, v105
	v_max_f32_e32 v104, 0, v104
	v_rcp_f32_e32 v100, v100
	v_add_f32_e32 v101, v101, v93
	v_mul_f32_e32 v101, 0xbfb8aa3b, v101
	v_exp_f32_e32 v101, v101
	s_nop 0
	v_add_f32_e32 v101, 1.0, v101
	v_add_f32_e32 v106, v106, v98
	v_mul_f32_e32 v106, 0xbfb8aa3b, v106
	v_exp_f32_e32 v106, v106
	s_waitcnt vmcnt(0) lgkmcnt(0)
	v_and_b32_e32 v114, 0xffff0000, v112
	v_lshlrev_b32_e32 v115, 16, v113
	v_sqrt_f32_e32 v104, v104
	s_nop 0
	v_mul_f32_e32 v100, v100, v104
	v_lshlrev_b32_e32 v104, 16, v112
	v_mul_f32_e32 v100, v100, v104
	v_rcp_f32_e32 v104, v118
	v_and_b32_e32 v121, 0xffff0000, v113
	v_mul_f32_e64 v122, v104, -v89
	v_mul_f32_e32 v104, -2.0, v122
	v_cvt_pk_bf16_f32 v100, v120, v100
	v_mul_f32_e32 v105, 0x3e4ccccd, v104
	v_fma_f32 v157, v104, s81, 1.0
	v_pk_mul_f32 v[112:113], v[104:105], v[156:157]
	v_mul_f32_e32 v123, 0x3eaaaaab, v104
	v_sub_f32_e32 v105, 1.0, v113
	v_fma_f32 v159, -v112, v105, 1.0
	v_mov_b32_e32 v105, v123
	v_pk_mul_f32 v[112:113], v[104:105], v[158:159]
	v_add_f32_e32 v102, v102, v94
	v_sub_f32_e32 v105, 1.0, v113
	v_fma_f32 v105, -v112, v105, 1.0
	v_mul_f32_e32 v104, v104, v105
	v_max_f32_e32 v104, 0, v104
	v_rcp_f32_e32 v101, v101
	v_mul_f32_e32 v102, 0xbfb8aa3b, v102
	v_exp_f32_e32 v102, v102
	v_add_f32_e32 v107, v107, v99
	v_add_f32_e32 v102, 1.0, v102
	v_mul_f32_e32 v107, 0xbfb8aa3b, v107
	v_exp_f32_e32 v107, v107
	v_add_f32_e32 v103, v103, v95
	v_mul_f32_e32 v103, 0xbfb8aa3b, v103
	v_sqrt_f32_e32 v104, v104
	v_add_f32_e32 v105, 1.0, v106
	v_mul_f32_e32 v101, v101, v104
	v_mul_f32_e32 v101, v101, v114
	v_exp_f32_e32 v103, v103
	v_rcp_f32_e32 v104, v105
	s_nop 0
	v_mul_f32_e64 v119, v104, -v90
	v_mul_f32_e32 v104, -2.0, v119
	v_mul_f32_e32 v105, 0x3e4ccccd, v104
	v_fma_f32 v157, v104, s81, 1.0
; DI unsigned pk2(float a, float b) { f32x2 v = {a, b}; bf16v2_t r = __builtin_convertvector(v, bf16v2_t); return __builtin_bit_cast(unsigned, r); }
; DI float sigm(float x) { return 1.f / (1.f + __expf(-x)); }
;     DI void operator()(const Acc& acc, const Unit& u, int wr, int wc, int fr, int fq, const float (&pre)[8]) const {
;     ...
;         for (int n = 0; n < 2; ++n) {
;             const f32x4 br = *(const f32x4*)(brg + f0 + 4 * n), bi = *(const f32x4*)(big + f0 + 4 * n), sp = *(const f32x4*)(sp8t + f0 + 4 * n);
; #pragma unroll
;             for (int ai = 0; ai < 2; ++ai)
; #pragma unroll
;                 for (int m = 0; m < 4; ++m) { const size_t o = (size_t)(row0 + ai * HALF + m * 16) * DM + f0 + 4 * n;
;                     const u32x2 xw = *(const u32x2*)(xc + o);
;                     const float xv[4] = {__uint_as_float(xw.x << 16), __uint_as_float(xw.x & 0xffff0000u), __uint_as_float(xw.y << 16), __uint_as_float(xw.y & 0xffff0000u)};
;                     u32x4 w;
; #pragma unroll
;                     for (int e = 0; e < 4; ++e) { const float r = sigm(acc[ai][0][m][n][e] + br[e]), ig = sigm(acc[ai][1][m][n][e] + bi[e]);
;                         const float la = -sp[e] * r, uu = -2.f * la;
;                         const float om = uu * (1.f - uu * 0.5f * (1.f - uu * (1.f / 3.f) * (1.f - uu * 0.25f * (1.f - uu * 0.2f * (1.f - uu * (1.f / 6.f))))));
;                         w[e] = pk2(la, sqrtf(fmaxf(om, 0.f)) * ig * xv[e]); }
;                     *(u32x4*)(ax + o) = w; __builtin_amdgcn_sched_barrier(0); }
	v_pk_mul_f32 v[112:113], v[104:105], v[156:157]
	v_mul_f32_e32 v120, 0x3eaaaaab, v104
	v_sub_f32_e32 v105, 1.0, v113
	v_fma_f32 v159, -v112, v105, 1.0
	v_mov_b32_e32 v105, v120
	v_pk_mul_f32 v[112:113], v[104:105], v[158:159]
	v_sub_f32_e32 v105, 1.0, v113
	v_fma_f32 v105, -v112, v105, 1.0
	v_mul_f32_e32 v104, v104, v105
	v_max_f32_e32 v104, 0, v104
	v_rcp_f32_e32 v102, v102
	v_add_f32_e32 v103, 1.0, v103
	v_cvt_pk_bf16_f32 v101, v122, v101
	v_sqrt_f32_e32 v104, v104
	v_add_f32_e32 v105, 1.0, v107
	v_mul_f32_e32 v102, v102, v104
	v_mul_f32_e32 v102, v102, v115
	v_cvt_pk_bf16_f32 v102, v119, v102
	v_rcp_f32_e32 v104, v105
	s_nop 0
	v_mul_f32_e64 v115, v104, -v91
	v_mul_f32_e32 v104, -2.0, v115
	v_mul_f32_e32 v105, 0x3e4ccccd, v104
	v_fma_f32 v157, v104, s81, 1.0
	v_pk_mul_f32 v[106:107], v[104:105], v[156:157]
	v_mul_f32_e32 v118, 0x3eaaaaab, v104
	v_sub_f32_e32 v105, 1.0, v107
	v_fma_f32 v159, -v106, v105, 1.0
	v_mov_b32_e32 v105, v118
	v_pk_mul_f32 v[106:107], v[104:105], v[158:159]
	s_nop 0
	v_sub_f32_e32 v105, 1.0, v107
	v_fma_f32 v105, -v106, v105, 1.0
	v_mul_f32_e32 v104, v104, v105
	v_max_f32_e32 v104, 0, v104
	v_rcp_f32_e32 v103, v103
	v_sqrt_f32_e32 v104, v104
	s_nop 0
	v_mul_f32_e32 v103, v103, v104
	v_mul_f32_e32 v103, v103, v121
	v_cvt_pk_bf16_f32 v103, v115, v103
	v_lshl_add_u64 v[104:105], v[110:111], 2, s[36:37]
	flat_store_dwordx4 v[104:105], v[100:103]
	s_nop 1
	v_lshl_add_u64 v[100:101], v[166:167], 0, s[44:45]
	v_lshl_add_u64 v[102:103], v[100:101], 0, v[160:161]
	v_lshl_add_u64 v[104:105], v[102:103], 1, s[16:17]
	flat_load_dwordx2 v[104:105], v[104:105]
	v_add_f32_e32 v84, v84, v96
	v_add_f32_e32 v85, v85, v97
	v_mul_f32_e32 v84, 0xbfb8aa3b, v84
	v_mul_f32_e32 v85, 0xbfb8aa3b, v85
	v_exp_f32_e32 v84, v84
	v_exp_f32_e32 v85, v85
	v_add_f32_e32 v80, v80, v92
	v_mul_f32_e32 v80, 0xbfb8aa3b, v80
	v_add_f32_e32 v84, 1.0, v84
	v_add_f32_e32 v110, 1.0, v85
	v_exp_f32_e32 v80, v80
	s_nop 0
	v_add_f32_e32 v80, 1.0, v80
	v_rcp_f32_e32 v84, v84
	s_nop 0
	v_mul_f32_e64 v112, v84, -v88
	v_mul_f32_e32 v84, -2.0, v112
	v_mul_f32_e32 v85, 0x3e4ccccd, v84
	v_fma_f32 v157, v84, s81, 1.0
	v_pk_mul_f32 v[106:107], v[84:85], v[156:157]
	v_mul_f32_e32 v118, 0x3eaaaaab, v84
	v_sub_f32_e32 v107, 1.0, v107
	v_mov_b32_e32 v85, v118
	v_fma_f32 v159, -v106, v107, 1.0
	v_pk_mul_f32 v[106:107], v[84:85], v[158:159]
	v_sub_f32_e32 v85, 1.0, v107
	v_fma_f32 v85, -v106, v85, 1.0
	v_mul_f32_e32 v84, v84, v85
	v_max_f32_e32 v84, 0, v84
	v_rcp_f32_e32 v80, v80
	v_add_f32_e32 v81, v81, v93
	v_mul_f32_e32 v81, 0xbfb8aa3b, v81
	v_exp_f32_e32 v81, v81
	s_nop 0
	v_add_f32_e32 v81, 1.0, v81
	v_add_f32_e32 v86, v86, v98
	v_mul_f32_e32 v86, 0xbfb8aa3b, v86
	v_exp_f32_e32 v86, v86
	s_waitcnt vmcnt(0) lgkmcnt(0)
	v_and_b32_e32 v106, 0xffff0000, v104
	v_lshlrev_b32_e32 v107, 16, v105
	v_sqrt_f32_e32 v84, v84
	s_nop 0
	v_mul_f32_e32 v80, v80, v84
	v_lshlrev_b32_e32 v84, 16, v104
	v_mul_f32_e32 v80, v80, v84
	v_rcp_f32_e32 v84, v110
	v_and_b32_e32 v113, 0xffff0000, v105
	v_mul_f32_e64 v114, v84, -v89
	v_mul_f32_e32 v84, -2.0, v114
	v_cvt_pk_bf16_f32 v80, v112, v80
	v_mul_f32_e32 v85, 0x3e4ccccd, v84
	v_fma_f32 v157, v84, s81, 1.0
	v_pk_mul_f32 v[104:105], v[84:85], v[156:157]
	v_mul_f32_e32 v115, 0x3eaaaaab, v84
	v_sub_f32_e32 v85, 1.0, v105
	v_fma_f32 v159, -v104, v85, 1.0
	v_mov_b32_e32 v85, v115
	v_pk_mul_f32 v[104:105], v[84:85], v[158:159]
	v_add_f32_e32 v82, v82, v94
	v_sub_f32_e32 v85, 1.0, v105
	v_fma_f32 v85, -v104, v85, 1.0
	v_mul_f32_e32 v84, v84, v85
	v_max_f32_e32 v84, 0, v84
	v_rcp_f32_e32 v81, v81
	v_mul_f32_e32 v82, 0xbfb8aa3b, v82
	v_exp_f32_e32 v82, v82
	v_add_f32_e32 v87, v87, v99
	v_add_f32_e32 v82, 1.0, v82
	v_mul_f32_e32 v87, 0xbfb8aa3b, v87
	v_exp_f32_e32 v87, v87
	v_add_f32_e32 v83, v83, v95
	v_mul_f32_e32 v83, 0xbfb8aa3b, v83
	v_sqrt_f32_e32 v84, v84
	v_add_f32_e32 v85, 1.0, v86
	v_mul_f32_e32 v81, v81, v84
	v_mul_f32_e32 v81, v81, v106
	v_exp_f32_e32 v83, v83
	v_rcp_f32_e32 v84, v85
	s_nop 0
	v_mul_f32_e64 v111, v84, -v90
	v_mul_f32_e32 v84, -2.0, v111
	v_mul_f32_e32 v85, 0x3e4ccccd, v84
	v_fma_f32 v157, v84, s81, 1.0
	v_pk_mul_f32 v[104:105], v[84:85], v[156:157]
	v_mul_f32_e32 v112, 0x3eaaaaab, v84
	v_sub_f32_e32 v85, 1.0, v105
	v_fma_f32 v159, -v104, v85, 1.0
	v_mov_b32_e32 v85, v112
	v_pk_mul_f32 v[104:105], v[84:85], v[158:159]
	v_sub_f32_e32 v85, 1.0, v105
	v_fma_f32 v85, -v104, v85, 1.0
	v_mul_f32_e32 v84, v84, v85
	v_max_f32_e32 v84, 0, v84
	v_rcp_f32_e32 v82, v82
	v_add_f32_e32 v83, 1.0, v83
	v_cvt_pk_bf16_f32 v81, v114, v81
	v_sqrt_f32_e32 v84, v84
	v_add_f32_e32 v85, 1.0, v87
	v_mul_f32_e32 v82, v82, v84
	v_mul_f32_e32 v82, v82, v107
	v_cvt_pk_bf16_f32 v82, v111, v82
	v_rcp_f32_e32 v84, v85
	s_nop 0
	v_mul_f32_e64 v107, v84, -v91
	v_mul_f32_e32 v84, -2.0, v107
	v_mul_f32_e32 v85, 0x3e4ccccd, v84
	v_fma_f32 v157, v84, s81, 1.0
	v_pk_mul_f32 v[86:87], v[84:85], v[156:157]
	v_mul_f32_e32 v110, 0x3eaaaaab, v84
	v_sub_f32_e32 v85, 1.0, v87
	v_fma_f32 v159, -v86, v85, 1.0
	v_mov_b32_e32 v85, v110
	v_pk_mul_f32 v[86:87], v[84:85], v[158:159]
	s_nop 0
	v_sub_f32_e32 v85, 1.0, v87
	v_fma_f32 v85, -v86, v85, 1.0
	v_mul_f32_e32 v84, v84, v85
	v_max_f32_e32 v84, 0, v84
	v_rcp_f32_e32 v83, v83
	v_sqrt_f32_e32 v84, v84
	s_nop 0
	v_mul_f32_e32 v83, v83, v84
	v_mul_f32_e32 v83, v83, v113
	v_cvt_pk_bf16_f32 v83, v107, v83
	v_lshl_add_u64 v[84:85], v[102:103], 2, s[36:37]
	flat_store_dwordx4 v[84:85], v[80:83]
	s_nop 1
	v_lshl_add_u64 v[80:81], v[166:167], 0, s[46:47]
	v_lshl_add_u64 v[82:83], v[80:81], 0, v[160:161]
	v_lshl_add_u64 v[84:85], v[82:83], 1, s[16:17]
	flat_load_dwordx2 v[84:85], v[84:85]
	v_add_f32_e32 v76, v76, v96
	v_add_f32_e32 v77, v77, v97
	v_mul_f32_e32 v76, 0xbfb8aa3b, v76
	v_mul_f32_e32 v77, 0xbfb8aa3b, v77
	v_exp_f32_e32 v76, v76
	v_exp_f32_e32 v77, v77
	v_add_f32_e32 v72, v72, v92
	v_mul_f32_e32 v72, 0xbfb8aa3b, v72
	v_add_f32_e32 v76, 1.0, v76
	v_add_f32_e32 v102, 1.0, v77
	v_exp_f32_e32 v72, v72
	s_nop 0
	v_add_f32_e32 v72, 1.0, v72
	v_rcp_f32_e32 v76, v76
	s_nop 0
	v_mul_f32_e64 v104, v76, -v88
	v_mul_f32_e32 v76, -2.0, v104
	v_mul_f32_e32 v77, 0x3e4ccccd, v76
	v_fma_f32 v157, v76, s81, 1.0
	v_pk_mul_f32 v[86:87], v[76:77], v[156:157]
	v_mul_f32_e32 v110, 0x3eaaaaab, v76
	v_sub_f32_e32 v87, 1.0, v87
	v_mov_b32_e32 v77, v110
	v_fma_f32 v159, -v86, v87, 1.0
	v_pk_mul_f32 v[86:87], v[76:77], v[158:159]
	v_sub_f32_e32 v77, 1.0, v87
	v_fma_f32 v77, -v86, v77, 1.0
	v_mul_f32_e32 v76, v76, v77
	v_max_f32_e32 v76, 0, v76
	v_rcp_f32_e32 v72, v72
	v_add_f32_e32 v73, v73, v93
	v_mul_f32_e32 v73, 0xbfb8aa3b, v73
	v_exp_f32_e32 v73, v73
	s_nop 0
	v_add_f32_e32 v73, 1.0, v73
	v_add_f32_e32 v78, v78, v98
	v_mul_f32_e32 v78, 0xbfb8aa3b, v78
	v_exp_f32_e32 v78, v78
	s_waitcnt vmcnt(0) lgkmcnt(0)
; DI unsigned pk2(float a, float b) { f32x2 v = {a, b}; bf16v2_t r = __builtin_convertvector(v, bf16v2_t); return __builtin_bit_cast(unsigned, r); }
; DI float sigm(float x) { return 1.f / (1.f + __expf(-x)); }
;     DI void operator()(const Acc& acc, const Unit& u, int wr, int wc, int fr, int fq, const float (&pre)[8]) const {
;     ...
;         for (int n = 0; n < 2; ++n) {
;             const f32x4 br = *(const f32x4*)(brg + f0 + 4 * n), bi = *(const f32x4*)(big + f0 + 4 * n), sp = *(const f32x4*)(sp8t + f0 + 4 * n);
; #pragma unroll
;             for (int ai = 0; ai < 2; ++ai)
; #pragma unroll
;                 for (int m = 0; m < 4; ++m) { const size_t o = (size_t)(row0 + ai * HALF + m * 16) * DM + f0 + 4 * n;
;                     const u32x2 xw = *(const u32x2*)(xc + o);
;                     const float xv[4] = {__uint_as_float(xw.x << 16), __uint_as_float(xw.x & 0xffff0000u), __uint_as_float(xw.y << 16), __uint_as_float(xw.y & 0xffff0000u)};
;                     u32x4 w;
; #pragma unroll
;                     for (int e = 0; e < 4; ++e) { const float r = sigm(acc[ai][0][m][n][e] + br[e]), ig = sigm(acc[ai][1][m][n][e] + bi[e]);
;                         const float la = -sp[e] * r, uu = -2.f * la;
;                         const float om = uu * (1.f - uu * 0.5f * (1.f - uu * (1.f / 3.f) * (1.f - uu * 0.25f * (1.f - uu * 0.2f * (1.f - uu * (1.f / 6.f))))));
;                         w[e] = pk2(la, sqrtf(fmaxf(om, 0.f)) * ig * xv[e]); }
;                     *(u32x4*)(ax + o) = w; __builtin_amdgcn_sched_barrier(0); }
	v_and_b32_e32 v86, 0xffff0000, v84
	v_lshlrev_b32_e32 v87, 16, v85
	v_sqrt_f32_e32 v76, v76
	s_nop 0
	v_mul_f32_e32 v72, v72, v76
	v_lshlrev_b32_e32 v76, 16, v84
	v_mul_f32_e32 v72, v72, v76
	v_rcp_f32_e32 v76, v102
	v_and_b32_e32 v105, 0xffff0000, v85
	v_mul_f32_e64 v106, v76, -v89
	v_mul_f32_e32 v76, -2.0, v106
	v_cvt_pk_bf16_f32 v72, v104, v72
	v_mul_f32_e32 v77, 0x3e4ccccd, v76
	v_fma_f32 v157, v76, s81, 1.0
	v_pk_mul_f32 v[84:85], v[76:77], v[156:157]
	v_mul_f32_e32 v107, 0x3eaaaaab, v76
	v_sub_f32_e32 v77, 1.0, v85
	v_fma_f32 v159, -v84, v77, 1.0
	v_mov_b32_e32 v77, v107
	v_pk_mul_f32 v[84:85], v[76:77], v[158:159]
	v_add_f32_e32 v74, v74, v94
	v_sub_f32_e32 v77, 1.0, v85
	v_fma_f32 v77, -v84, v77, 1.0
	v_mul_f32_e32 v76, v76, v77
	v_max_f32_e32 v76, 0, v76
	v_rcp_f32_e32 v73, v73
	v_mul_f32_e32 v74, 0xbfb8aa3b, v74
	v_exp_f32_e32 v74, v74
	v_add_f32_e32 v79, v79, v99
	v_add_f32_e32 v74, 1.0, v74
	v_mul_f32_e32 v79, 0xbfb8aa3b, v79
	v_exp_f32_e32 v79, v79
	v_add_f32_e32 v75, v75, v95
	v_mul_f32_e32 v75, 0xbfb8aa3b, v75
	v_sqrt_f32_e32 v76, v76
	v_add_f32_e32 v77, 1.0, v78
	v_mul_f32_e32 v73, v73, v76
	v_mul_f32_e32 v73, v73, v86
	v_exp_f32_e32 v75, v75
	v_rcp_f32_e32 v76, v77
	s_nop 0
	v_mul_f32_e64 v103, v76, -v90
	v_mul_f32_e32 v76, -2.0, v103
	v_mul_f32_e32 v77, 0x3e4ccccd, v76
	v_fma_f32 v157, v76, s81, 1.0
	v_pk_mul_f32 v[84:85], v[76:77], v[156:157]
	v_mul_f32_e32 v104, 0x3eaaaaab, v76
	v_sub_f32_e32 v77, 1.0, v85
	v_fma_f32 v159, -v84, v77, 1.0
	v_mov_b32_e32 v77, v104
	v_pk_mul_f32 v[84:85], v[76:77], v[158:159]
	v_sub_f32_e32 v77, 1.0, v85
	v_fma_f32 v77, -v84, v77, 1.0
	v_mul_f32_e32 v76, v76, v77
	v_max_f32_e32 v76, 0, v76
	v_rcp_f32_e32 v74, v74
	v_add_f32_e32 v75, 1.0, v75
	v_cvt_pk_bf16_f32 v73, v106, v73
	v_sqrt_f32_e32 v76, v76
	v_add_f32_e32 v77, 1.0, v79
	v_mul_f32_e32 v74, v74, v76
	v_mul_f32_e32 v74, v74, v87
	v_cvt_pk_bf16_f32 v74, v103, v74
	v_rcp_f32_e32 v76, v77
	s_nop 0
	v_mul_f32_e64 v87, v76, -v91
	v_mul_f32_e32 v76, -2.0, v87
	v_mul_f32_e32 v77, 0x3e4ccccd, v76
	v_fma_f32 v157, v76, s81, 1.0
	v_pk_mul_f32 v[78:79], v[76:77], v[156:157]
	v_mul_f32_e32 v102, 0x3eaaaaab, v76
	v_sub_f32_e32 v77, 1.0, v79
	v_fma_f32 v159, -v78, v77, 1.0
	v_mov_b32_e32 v77, v102
	v_pk_mul_f32 v[78:79], v[76:77], v[158:159]
	s_nop 0
	v_sub_f32_e32 v77, 1.0, v79
	v_fma_f32 v77, -v78, v77, 1.0
	v_mul_f32_e32 v76, v76, v77
	v_max_f32_e32 v76, 0, v76
	v_rcp_f32_e32 v75, v75
	v_sqrt_f32_e32 v76, v76
	s_nop 0
	v_mul_f32_e32 v75, v75, v76
	v_mul_f32_e32 v75, v75, v105
	v_cvt_pk_bf16_f32 v75, v87, v75
	v_lshl_add_u64 v[76:77], v[82:83], 2, s[36:37]
	flat_store_dwordx4 v[76:77], v[72:75]
	s_nop 1
	v_lshl_add_u64 v[76:77], v[166:167], 0, s[48:49]
	s_nop 0
	v_lshl_add_u64 v[72:73], v[76:77], 0, v[160:161]
	v_lshl_add_u64 v[74:75], v[72:73], 1, s[16:17]
	flat_load_dwordx2 v[74:75], v[74:75]
	v_add_f32_e32 v68, v68, v96
	v_add_f32_e32 v69, v69, v97
	v_mul_f32_e32 v68, 0xbfb8aa3b, v68
	v_mul_f32_e32 v69, 0xbfb8aa3b, v69
	v_exp_f32_e32 v68, v68
	v_exp_f32_e32 v69, v69
	v_add_f32_e32 v64, v64, v92
	v_mul_f32_e32 v64, 0xbfb8aa3b, v64
	v_add_f32_e32 v68, 1.0, v68
	v_add_f32_e32 v82, 1.0, v69
	v_exp_f32_e32 v64, v64
	s_nop 0
	v_add_f32_e32 v64, 1.0, v64
	v_rcp_f32_e32 v68, v68
	s_nop 0
	v_mul_f32_e64 v84, v68, -v88
	v_mul_f32_e32 v68, -2.0, v84
	v_mul_f32_e32 v69, 0x3e4ccccd, v68
	v_fma_f32 v157, v68, s81, 1.0
	v_pk_mul_f32 v[78:79], v[68:69], v[156:157]
	v_mul_f32_e32 v88, 0x3eaaaaab, v68
	v_sub_f32_e32 v79, 1.0, v79
	v_mov_b32_e32 v69, v88
	v_fma_f32 v159, -v78, v79, 1.0
	v_pk_mul_f32 v[78:79], v[68:69], v[158:159]
	v_sub_f32_e32 v69, 1.0, v79
	v_fma_f32 v69, -v78, v69, 1.0
	v_mul_f32_e32 v68, v68, v69
	v_max_f32_e32 v68, 0, v68
	v_rcp_f32_e32 v64, v64
	v_add_f32_e32 v65, v65, v93
	v_mul_f32_e32 v65, 0xbfb8aa3b, v65
	v_exp_f32_e32 v65, v65
	s_nop 0
	v_add_f32_e32 v65, 1.0, v65
	v_add_f32_e32 v70, v70, v98
	v_mul_f32_e32 v70, 0xbfb8aa3b, v70
	v_exp_f32_e32 v70, v70
	s_waitcnt vmcnt(0) lgkmcnt(0)
	v_and_b32_e32 v78, 0xffff0000, v74
	v_lshlrev_b32_e32 v79, 16, v75
	v_sqrt_f32_e32 v68, v68
	s_nop 0
	v_mul_f32_e32 v64, v64, v68
	v_lshlrev_b32_e32 v68, 16, v74
	v_mul_f32_e32 v64, v64, v68
	v_rcp_f32_e32 v68, v82
	v_and_b32_e32 v85, 0xffff0000, v75
	v_mul_f32_e64 v86, v68, -v89
	v_mul_f32_e32 v68, -2.0, v86
	v_cvt_pk_bf16_f32 v64, v84, v64
	v_mul_f32_e32 v69, 0x3e4ccccd, v68
	v_fma_f32 v157, v68, s81, 1.0
	v_pk_mul_f32 v[74:75], v[68:69], v[156:157]
	v_mul_f32_e32 v87, 0x3eaaaaab, v68
	v_sub_f32_e32 v69, 1.0, v75
	v_fma_f32 v159, -v74, v69, 1.0
	v_mov_b32_e32 v69, v87
	v_pk_mul_f32 v[74:75], v[68:69], v[158:159]
	v_add_f32_e32 v66, v66, v94
	v_sub_f32_e32 v69, 1.0, v75
	v_fma_f32 v69, -v74, v69, 1.0
	v_mul_f32_e32 v68, v68, v69
	v_max_f32_e32 v68, 0, v68
	v_rcp_f32_e32 v65, v65
	v_mul_f32_e32 v66, 0xbfb8aa3b, v66
	v_exp_f32_e32 v66, v66
	v_add_f32_e32 v71, v71, v99
	v_add_f32_e32 v66, 1.0, v66
	v_mul_f32_e32 v71, 0xbfb8aa3b, v71
	v_exp_f32_e32 v71, v71
	v_add_f32_e32 v67, v67, v95
	v_mul_f32_e32 v67, 0xbfb8aa3b, v67
	v_sqrt_f32_e32 v68, v68
	v_add_f32_e32 v69, 1.0, v70
	v_mul_f32_e32 v65, v65, v68
	v_mul_f32_e32 v65, v65, v78
	v_exp_f32_e32 v67, v67
	v_rcp_f32_e32 v68, v69
	s_nop 0
	v_mul_f32_e64 v83, v68, -v90
	v_mul_f32_e32 v68, -2.0, v83
	v_mul_f32_e32 v69, 0x3e4ccccd, v68
	v_fma_f32 v157, v68, s81, 1.0
	v_pk_mul_f32 v[74:75], v[68:69], v[156:157]
	v_mul_f32_e32 v84, 0x3eaaaaab, v68
	v_sub_f32_e32 v69, 1.0, v75
	v_fma_f32 v159, -v74, v69, 1.0
	v_mov_b32_e32 v69, v84
	v_pk_mul_f32 v[74:75], v[68:69], v[158:159]
	v_sub_f32_e32 v69, 1.0, v75
	v_fma_f32 v69, -v74, v69, 1.0
	v_mul_f32_e32 v68, v68, v69
	v_max_f32_e32 v68, 0, v68
	v_rcp_f32_e32 v66, v66
	v_add_f32_e32 v67, 1.0, v67
	v_cvt_pk_bf16_f32 v65, v86, v65
	v_sqrt_f32_e32 v68, v68
	v_add_f32_e32 v69, 1.0, v71
	v_mul_f32_e32 v66, v66, v68
	v_mul_f32_e32 v66, v66, v79
	v_cvt_pk_bf16_f32 v66, v83, v66
	v_rcp_f32_e32 v68, v69
	s_nop 0
	v_mul_f32_e64 v79, v68, -v91
	v_mul_f32_e32 v68, -2.0, v79
	v_mul_f32_e32 v69, 0x3e4ccccd, v68
	v_fma_f32 v157, v68, s81, 1.0
	v_pk_mul_f32 v[70:71], v[68:69], v[156:157]
	v_mul_f32_e32 v82, 0x3eaaaaab, v68
	v_sub_f32_e32 v69, 1.0, v71
	v_fma_f32 v159, -v70, v69, 1.0
	v_mov_b32_e32 v69, v82
	v_pk_mul_f32 v[70:71], v[68:69], v[158:159]
	s_nop 0
	v_sub_f32_e32 v69, 1.0, v71
	v_fma_f32 v69, -v70, v69, 1.0
	v_mul_f32_e32 v68, v68, v69
	v_max_f32_e32 v68, 0, v68
	v_rcp_f32_e32 v67, v67
	v_sqrt_f32_e32 v68, v68
	s_nop 0
	v_mul_f32_e32 v67, v67, v68
	v_mul_f32_e32 v67, v67, v85
	v_cvt_pk_bf16_f32 v67, v79, v67
	v_lshl_add_u64 v[68:69], v[72:73], 2, s[36:37]
	flat_store_dwordx4 v[68:69], v[64:67]
	global_load_dwordx4 v[72:75], v[162:163], off offset:16
	s_nop 0
	global_load_dwordx4 v[68:71], v[164:165], off offset:16
	v_or_b32_e32 v160, 4, v160
	v_lshl_add_u64 v[78:79], v[166:167], 0, v[160:161]
	v_lshl_add_u64 v[64:65], v[78:79], 1, s[16:17]
	flat_load_dwordx2 v[82:83], v[64:65]
	s_nop 0
	flat_load_dwordx4 v[64:67], v[168:169] offset:16
	s_waitcnt vmcnt(0)
; DI unsigned pk2(float a, float b) { f32x2 v = {a, b}; bf16v2_t r = __builtin_convertvector(v, bf16v2_t); return __builtin_bit_cast(unsigned, r); }
; DI float sigm(float x) { return 1.f / (1.f + __expf(-x)); }
;     DI void operator()(const Acc& acc, const Unit& u, int wr, int wc, int fr, int fq, const float (&pre)[8]) const {
;     ...
;         for (int n = 0; n < 2; ++n) {
;             const f32x4 br = *(const f32x4*)(brg + f0 + 4 * n), bi = *(const f32x4*)(big + f0 + 4 * n), sp = *(const f32x4*)(sp8t + f0 + 4 * n);
; #pragma unroll
;             for (int ai = 0; ai < 2; ++ai)
; #pragma unroll
;                 for (int m = 0; m < 4; ++m) { const size_t o = (size_t)(row0 + ai * HALF + m * 16) * DM + f0 + 4 * n;
;                     const u32x2 xw = *(const u32x2*)(xc + o);
;                     const float xv[4] = {__uint_as_float(xw.x << 16), __uint_as_float(xw.x & 0xffff0000u), __uint_as_float(xw.y << 16), __uint_as_float(xw.y & 0xffff0000u)};
;                     u32x4 w;
; #pragma unroll
;                     for (int e = 0; e < 4; ++e) { const float r = sigm(acc[ai][0][m][n][e] + br[e]), ig = sigm(acc[ai][1][m][n][e] + bi[e]);
;                         const float la = -sp[e] * r, uu = -2.f * la;
;                         const float om = uu * (1.f - uu * 0.5f * (1.f - uu * (1.f / 3.f) * (1.f - uu * 0.25f * (1.f - uu * 0.2f * (1.f - uu * (1.f / 6.f))))));
;                         w[e] = pk2(la, sqrtf(fmaxf(om, 0.f)) * ig * xv[e]); }
;                     *(u32x4*)(ax + o) = w; __builtin_amdgcn_sched_barrier(0); }
	v_add_f32_e32 v60, v60, v72
	v_add_f32_e32 v57, v57, v69
	v_mul_f32_e32 v60, 0xbfb8aa3b, v60
	v_add_f32_e32 v56, v56, v68
	v_mul_f32_e32 v57, 0xbfb8aa3b, v57
	v_exp_f32_e32 v60, v60
	v_add_f32_e32 v61, v61, v73
	v_mul_f32_e32 v56, 0xbfb8aa3b, v56
	v_exp_f32_e32 v57, v57
	v_mul_f32_e32 v61, 0xbfb8aa3b, v61
	v_exp_f32_e32 v56, v56
	v_exp_f32_e32 v61, v61
	v_add_f32_e32 v60, 1.0, v60
	v_add_f32_e32 v90, 1.0, v57
	v_add_f32_e32 v56, 1.0, v56
	s_waitcnt lgkmcnt(0)
	v_lshlrev_b32_e32 v88, 16, v83
	v_and_b32_e32 v89, 0xffff0000, v83
	v_add_f32_e32 v61, 1.0, v61
	v_lshlrev_b32_e32 v86, 16, v82
	v_and_b32_e32 v87, 0xffff0000, v82
	v_rcp_f32_e32 v57, v60
	s_nop 0
	v_mul_f32_e64 v93, v57, -v64
	v_rcp_f32_e32 v92, v56
	v_mul_f32_e32 v56, -2.0, v93
	v_rcp_f32_e32 v60, v61
	v_mul_f32_e32 v57, 0x3e4ccccd, v56
	v_fma_f32 v157, v56, s81, 1.0
	v_mul_f32_e32 v82, 0x3eaaaaab, v56
	v_mul_f32_e64 v94, v60, -v65
	v_pk_mul_f32 v[60:61], v[56:57], v[156:157]
	v_mov_b32_e32 v57, v82
	v_mul_f32_e32 v82, -2.0, v94
	v_sub_f32_e32 v61, 1.0, v61
	v_mul_f32_e32 v84, 0x3eaaaaab, v82
	v_mul_f32_e32 v83, 0x3e4ccccd, v82
	v_fma_f32 v157, v82, s81, 1.0
	v_fma_f32 v159, -v60, v61, 1.0
	v_pk_mul_f32 v[60:61], v[82:83], v[156:157]
	v_mov_b32_e32 v83, v84
	v_pk_mul_f32 v[84:85], v[56:57], v[158:159]
	v_sub_f32_e32 v57, 1.0, v61
	v_sub_f32_e32 v61, 1.0, v85
	v_fma_f32 v159, -v60, v57, 1.0
	v_fma_f32 v57, -v84, v61, 1.0
	v_mul_f32_e32 v56, v56, v57
	v_pk_mul_f32 v[60:61], v[82:83], v[158:159]
	v_max_f32_e32 v56, 0, v56
	v_sub_f32_e32 v57, 1.0, v61
	v_mul_f32_e32 v61, 0x4f800000, v56
	v_cmp_gt_f32_e32 vcc, s82, v56
	v_fma_f32 v57, -v60, v57, 1.0
	v_mul_f32_e32 v57, v82, v57
	v_cndmask_b32_e32 v56, v56, v61, vcc
	v_sqrt_f32_e32 v61, v56
	v_max_f32_e32 v57, 0, v57
	v_add_f32_e32 v62, v62, v74
	v_mul_f32_e32 v62, 0xbfb8aa3b, v62
	v_add_u32_e32 v60, -1, v61
	v_add_u32_e32 v82, 1, v61
	v_fma_f32 v83, -v60, v61, v56
	v_fma_f32 v84, -v82, v61, v56
	v_cmp_ge_f32_e64 s[12:13], 0, v83
	v_exp_f32_e32 v62, v62
	v_add_f32_e32 v58, v58, v70
	v_cndmask_b32_e64 v60, v61, v60, s[12:13]
	v_cmp_lt_f32_e64 s[12:13], 0, v84
	v_mul_f32_e32 v58, 0xbfb8aa3b, v58
	v_exp_f32_e32 v58, v58
	v_cndmask_b32_e64 v60, v60, v82, s[12:13]
	v_mul_f32_e32 v61, 0x37800000, v60
	v_cndmask_b32_e32 v60, v60, v61, vcc
	v_cmp_class_f32_e32 vcc, v56, v182
	v_add_f32_e32 v58, 1.0, v58
	s_nop 0
	v_cndmask_b32_e32 v56, v60, v56, vcc
	v_rcp_f32_e32 v61, v90
	v_mul_f32_e32 v56, v92, v56
	v_mul_f32_e32 v56, v56, v86
	v_add_f32_e32 v63, v63, v75
	v_mul_f32_e32 v63, 0xbfb8aa3b, v63
	v_exp_f32_e32 v63, v63
	v_sqrt_f32_e32 v57, v57
	v_add_f32_e32 v60, 1.0, v62
	v_mul_f32_e32 v57, v61, v57
	v_mul_f32_e32 v57, v57, v87
	v_add_f32_e32 v59, v59, v71
	v_rcp_f32_e32 v60, v60
	s_nop 0
	v_mul_f32_e64 v86, v60, -v66
	v_mul_f32_e32 v60, -2.0, v86
	v_mul_f32_e32 v61, 0x3e4ccccd, v60
	v_fma_f32 v157, v60, s81, 1.0
	v_pk_mul_f32 v[82:83], v[60:61], v[156:157]
	v_mul_f32_e32 v87, 0x3eaaaaab, v60
	v_sub_f32_e32 v61, 1.0, v83
	v_fma_f32 v159, -v82, v61, 1.0
	v_mov_b32_e32 v61, v87
	v_pk_mul_f32 v[82:83], v[60:61], v[158:159]
	v_sub_f32_e32 v61, 1.0, v83
	v_fma_f32 v61, -v82, v61, 1.0
	v_mul_f32_e32 v60, v60, v61
	v_max_f32_e32 v60, 0, v60
	v_rcp_f32_e32 v58, v58
	v_mul_f32_e32 v59, 0xbfb8aa3b, v59
	v_exp_f32_e32 v59, v59
	v_cvt_pk_bf16_f32 v56, v93, v56
	v_cvt_pk_bf16_f32 v57, v94, v57
	v_add_f32_e32 v59, 1.0, v59
	v_sqrt_f32_e32 v60, v60
	v_add_f32_e32 v61, 1.0, v63
	v_mul_f32_e32 v58, v58, v60
	v_mul_f32_e32 v58, v58, v88
	v_cvt_pk_bf16_f32 v58, v86, v58
	v_rcp_f32_e32 v60, v61
	s_nop 0
	v_mul_f32_e64 v85, v60, -v67
	v_mul_f32_e32 v60, -2.0, v85
	v_mul_f32_e32 v61, 0x3e4ccccd, v60
	v_fma_f32 v157, v60, s81, 1.0
	v_pk_mul_f32 v[62:63], v[60:61], v[156:157]
	v_mul_f32_e32 v86, 0x3eaaaaab, v60
	v_sub_f32_e32 v61, 1.0, v63
	v_fma_f32 v159, -v62, v61, 1.0
	v_mov_b32_e32 v61, v86
	v_pk_mul_f32 v[62:63], v[60:61], v[158:159]
	s_nop 0
	v_sub_f32_e32 v61, 1.0, v63
	v_fma_f32 v61, -v62, v61, 1.0
	v_mul_f32_e32 v60, v60, v61
	v_max_f32_e32 v60, 0, v60
	v_rcp_f32_e32 v59, v59
	v_sqrt_f32_e32 v60, v60
	s_nop 0
	v_mul_f32_e32 v59, v59, v60
	v_mul_f32_e32 v59, v59, v89
	v_cvt_pk_bf16_f32 v59, v85, v59
	v_lshl_add_u64 v[60:61], v[78:79], 2, s[36:37]
	flat_store_dwordx4 v[60:61], v[56:59]
	s_nop 1
	v_lshl_add_u64 v[56:57], v[132:133], 0, v[160:161]
	v_lshl_add_u64 v[58:59], v[56:57], 1, s[16:17]
	flat_load_dwordx2 v[58:59], v[58:59]
	v_add_f32_e32 v52, v52, v72
	v_add_f32_e32 v53, v53, v73
	v_mul_f32_e32 v52, 0xbfb8aa3b, v52
	v_mul_f32_e32 v53, 0xbfb8aa3b, v53
	v_exp_f32_e32 v52, v52
	v_exp_f32_e32 v53, v53
	v_add_f32_e32 v48, v48, v68
	v_mul_f32_e32 v48, 0xbfb8aa3b, v48
	v_add_f32_e32 v52, 1.0, v52
	v_add_f32_e32 v62, 1.0, v53
	v_exp_f32_e32 v48, v48
	s_nop 0
	v_add_f32_e32 v48, 1.0, v48
	v_rcp_f32_e32 v52, v52
	s_nop 0
	v_mul_f32_e64 v78, v52, -v64
	v_mul_f32_e32 v52, -2.0, v78
	v_mul_f32_e32 v53, 0x3e4ccccd, v52
	v_fma_f32 v157, v52, s81, 1.0
	v_pk_mul_f32 v[60:61], v[52:53], v[156:157]
	v_mul_f32_e32 v84, 0x3eaaaaab, v52
	v_sub_f32_e32 v61, 1.0, v61
	v_mov_b32_e32 v53, v84
	v_fma_f32 v159, -v60, v61, 1.0
	v_pk_mul_f32 v[60:61], v[52:53], v[158:159]
	v_sub_f32_e32 v53, 1.0, v61
	v_fma_f32 v53, -v60, v53, 1.0
	v_mul_f32_e32 v52, v52, v53
	v_max_f32_e32 v52, 0, v52
	v_rcp_f32_e32 v48, v48
	v_add_f32_e32 v49, v49, v69
	v_mul_f32_e32 v49, 0xbfb8aa3b, v49
	v_exp_f32_e32 v49, v49
	s_nop 0
	v_add_f32_e32 v49, 1.0, v49
	v_add_f32_e32 v54, v54, v74
	v_mul_f32_e32 v54, 0xbfb8aa3b, v54
	v_exp_f32_e32 v54, v54
	s_waitcnt vmcnt(0) lgkmcnt(0)
; DI unsigned pk2(float a, float b) { f32x2 v = {a, b}; bf16v2_t r = __builtin_convertvector(v, bf16v2_t); return __builtin_bit_cast(unsigned, r); }
; DI float sigm(float x) { return 1.f / (1.f + __expf(-x)); }
;     DI void operator()(const Acc& acc, const Unit& u, int wr, int wc, int fr, int fq, const float (&pre)[8]) const {
;     ...
;         for (int n = 0; n < 2; ++n) {
;             const f32x4 br = *(const f32x4*)(brg + f0 + 4 * n), bi = *(const f32x4*)(big + f0 + 4 * n), sp = *(const f32x4*)(sp8t + f0 + 4 * n);
; #pragma unroll
;             for (int ai = 0; ai < 2; ++ai)
; #pragma unroll
;                 for (int m = 0; m < 4; ++m) { const size_t o = (size_t)(row0 + ai * HALF + m * 16) * DM + f0 + 4 * n;
;                     const u32x2 xw = *(const u32x2*)(xc + o);
;                     const float xv[4] = {__uint_as_float(xw.x << 16), __uint_as_float(xw.x & 0xffff0000u), __uint_as_float(xw.y << 16), __uint_as_float(xw.y & 0xffff0000u)};
;                     u32x4 w;
; #pragma unroll
;                     for (int e = 0; e < 4; ++e) { const float r = sigm(acc[ai][0][m][n][e] + br[e]), ig = sigm(acc[ai][1][m][n][e] + bi[e]);
;                         const float la = -sp[e] * r, uu = -2.f * la;
;                         const float om = uu * (1.f - uu * 0.5f * (1.f - uu * (1.f / 3.f) * (1.f - uu * 0.25f * (1.f - uu * 0.2f * (1.f - uu * (1.f / 6.f))))));
;                         w[e] = pk2(la, sqrtf(fmaxf(om, 0.f)) * ig * xv[e]); }
;                     *(u32x4*)(ax + o) = w; __builtin_amdgcn_sched_barrier(0); }
	v_and_b32_e32 v60, 0xffff0000, v58
	v_lshlrev_b32_e32 v61, 16, v59
	v_sqrt_f32_e32 v52, v52
	s_nop 0
	v_mul_f32_e32 v48, v48, v52
	v_lshlrev_b32_e32 v52, 16, v58
	v_mul_f32_e32 v48, v48, v52
	v_rcp_f32_e32 v52, v62
	v_and_b32_e32 v79, 0xffff0000, v59
	v_mul_f32_e64 v82, v52, -v65
	v_mul_f32_e32 v52, -2.0, v82
	v_cvt_pk_bf16_f32 v48, v78, v48
	v_mul_f32_e32 v53, 0x3e4ccccd, v52
	v_fma_f32 v157, v52, s81, 1.0
	v_pk_mul_f32 v[58:59], v[52:53], v[156:157]
	v_mul_f32_e32 v83, 0x3eaaaaab, v52
	v_sub_f32_e32 v53, 1.0, v59
	v_fma_f32 v159, -v58, v53, 1.0
	v_mov_b32_e32 v53, v83
	v_pk_mul_f32 v[58:59], v[52:53], v[158:159]
	v_add_f32_e32 v50, v50, v70
	v_sub_f32_e32 v53, 1.0, v59
	v_fma_f32 v53, -v58, v53, 1.0
	v_mul_f32_e32 v52, v52, v53
	v_max_f32_e32 v52, 0, v52
	v_rcp_f32_e32 v49, v49
	v_mul_f32_e32 v50, 0xbfb8aa3b, v50
	v_exp_f32_e32 v50, v50
	v_add_f32_e32 v55, v55, v75
	v_add_f32_e32 v50, 1.0, v50
	v_mul_f32_e32 v55, 0xbfb8aa3b, v55
	v_exp_f32_e32 v55, v55
	v_add_f32_e32 v51, v51, v71
	v_mul_f32_e32 v51, 0xbfb8aa3b, v51
	v_sqrt_f32_e32 v52, v52
	v_add_f32_e32 v53, 1.0, v54
	v_mul_f32_e32 v49, v49, v52
	v_mul_f32_e32 v49, v49, v60
	v_exp_f32_e32 v51, v51
	v_rcp_f32_e32 v52, v53
	s_nop 0
	v_mul_f32_e64 v63, v52, -v66
	v_mul_f32_e32 v52, -2.0, v63
	v_mul_f32_e32 v53, 0x3e4ccccd, v52
	v_fma_f32 v157, v52, s81, 1.0
	v_pk_mul_f32 v[58:59], v[52:53], v[156:157]
	v_mul_f32_e32 v78, 0x3eaaaaab, v52
	v_sub_f32_e32 v53, 1.0, v59
	v_fma_f32 v159, -v58, v53, 1.0
	v_mov_b32_e32 v53, v78
	v_pk_mul_f32 v[58:59], v[52:53], v[158:159]
	v_sub_f32_e32 v53, 1.0, v59
	v_fma_f32 v53, -v58, v53, 1.0
	v_mul_f32_e32 v52, v52, v53
	v_max_f32_e32 v52, 0, v52
	v_rcp_f32_e32 v50, v50
	v_add_f32_e32 v51, 1.0, v51
	v_cvt_pk_bf16_f32 v49, v82, v49
	v_sqrt_f32_e32 v52, v52
	v_add_f32_e32 v53, 1.0, v55
	v_mul_f32_e32 v50, v50, v52
	v_mul_f32_e32 v50, v50, v61
	v_cvt_pk_bf16_f32 v50, v63, v50
	v_rcp_f32_e32 v52, v53
	s_nop 0
	v_mul_f32_e64 v61, v52, -v67
	v_mul_f32_e32 v52, -2.0, v61
	v_mul_f32_e32 v53, 0x3e4ccccd, v52
	v_fma_f32 v157, v52, s81, 1.0
	v_pk_mul_f32 v[54:55], v[52:53], v[156:157]
	v_mul_f32_e32 v62, 0x3eaaaaab, v52
	v_sub_f32_e32 v53, 1.0, v55
	v_fma_f32 v159, -v54, v53, 1.0
	v_mov_b32_e32 v53, v62
	v_pk_mul_f32 v[54:55], v[52:53], v[158:159]
	s_nop 0
	v_sub_f32_e32 v53, 1.0, v55
	v_fma_f32 v53, -v54, v53, 1.0
	v_mul_f32_e32 v52, v52, v53
	v_max_f32_e32 v52, 0, v52
	v_rcp_f32_e32 v51, v51
	v_sqrt_f32_e32 v52, v52
	s_nop 0
	v_mul_f32_e32 v51, v51, v52
	v_mul_f32_e32 v51, v51, v79
	v_cvt_pk_bf16_f32 v51, v61, v51
	v_lshl_add_u64 v[52:53], v[56:57], 2, s[36:37]
	flat_store_dwordx4 v[52:53], v[48:51]
	s_nop 1
	v_lshl_add_u64 v[48:49], v[124:125], 0, v[160:161]
	v_lshl_add_u64 v[50:51], v[48:49], 1, s[16:17]
	flat_load_dwordx2 v[50:51], v[50:51]
	v_add_f32_e32 v44, v44, v72
	v_add_f32_e32 v45, v45, v73
	v_mul_f32_e32 v44, 0xbfb8aa3b, v44
	v_mul_f32_e32 v45, 0xbfb8aa3b, v45
	v_exp_f32_e32 v44, v44
	v_exp_f32_e32 v45, v45
	v_add_f32_e32 v40, v40, v68
	v_mul_f32_e32 v40, 0xbfb8aa3b, v40
	v_add_f32_e32 v44, 1.0, v44
	v_add_f32_e32 v54, 1.0, v45
	v_exp_f32_e32 v40, v40
	s_nop 0
	v_add_f32_e32 v40, 1.0, v40
	v_rcp_f32_e32 v44, v44
	s_nop 0
	v_mul_f32_e64 v56, v44, -v64
	v_mul_f32_e32 v44, -2.0, v56
	v_mul_f32_e32 v45, 0x3e4ccccd, v44
	v_fma_f32 v157, v44, s81, 1.0
	v_pk_mul_f32 v[52:53], v[44:45], v[156:157]
	v_mul_f32_e32 v60, 0x3eaaaaab, v44
	v_sub_f32_e32 v53, 1.0, v53
	v_mov_b32_e32 v45, v60
	v_fma_f32 v159, -v52, v53, 1.0
	v_pk_mul_f32 v[52:53], v[44:45], v[158:159]
	v_sub_f32_e32 v45, 1.0, v53
	v_fma_f32 v45, -v52, v45, 1.0
	v_mul_f32_e32 v44, v44, v45
	v_max_f32_e32 v44, 0, v44
	v_rcp_f32_e32 v40, v40
	v_add_f32_e32 v41, v41, v69
	v_mul_f32_e32 v41, 0xbfb8aa3b, v41
	v_exp_f32_e32 v41, v41
	s_nop 0
	v_add_f32_e32 v41, 1.0, v41
	v_add_f32_e32 v46, v46, v74
	v_mul_f32_e32 v46, 0xbfb8aa3b, v46
	v_exp_f32_e32 v46, v46
	s_waitcnt vmcnt(0) lgkmcnt(0)
	v_and_b32_e32 v52, 0xffff0000, v50
	v_lshlrev_b32_e32 v53, 16, v51
	v_sqrt_f32_e32 v44, v44
	s_nop 0
	v_mul_f32_e32 v40, v40, v44
	v_lshlrev_b32_e32 v44, 16, v50
	v_mul_f32_e32 v40, v40, v44
	v_rcp_f32_e32 v44, v54
	v_and_b32_e32 v57, 0xffff0000, v51
	v_mul_f32_e64 v58, v44, -v65
	v_mul_f32_e32 v44, -2.0, v58
	v_cvt_pk_bf16_f32 v40, v56, v40
	v_mul_f32_e32 v45, 0x3e4ccccd, v44
	v_fma_f32 v157, v44, s81, 1.0
	v_pk_mul_f32 v[50:51], v[44:45], v[156:157]
	v_mul_f32_e32 v59, 0x3eaaaaab, v44
	v_sub_f32_e32 v45, 1.0, v51
	v_fma_f32 v159, -v50, v45, 1.0
	v_mov_b32_e32 v45, v59
	v_pk_mul_f32 v[50:51], v[44:45], v[158:159]
	v_add_f32_e32 v42, v42, v70
	v_sub_f32_e32 v45, 1.0, v51
	v_fma_f32 v45, -v50, v45, 1.0
	v_mul_f32_e32 v44, v44, v45
	v_max_f32_e32 v44, 0, v44
	v_rcp_f32_e32 v41, v41
	v_mul_f32_e32 v42, 0xbfb8aa3b, v42
	v_exp_f32_e32 v42, v42
	v_add_f32_e32 v47, v47, v75
	v_add_f32_e32 v42, 1.0, v42
	v_mul_f32_e32 v47, 0xbfb8aa3b, v47
	v_exp_f32_e32 v47, v47
	v_add_f32_e32 v43, v43, v71
	v_mul_f32_e32 v43, 0xbfb8aa3b, v43
	v_sqrt_f32_e32 v44, v44
	v_add_f32_e32 v45, 1.0, v46
	v_mul_f32_e32 v41, v41, v44
	v_mul_f32_e32 v41, v41, v52
	v_exp_f32_e32 v43, v43
	v_rcp_f32_e32 v44, v45
	s_nop 0
	v_mul_f32_e64 v55, v44, -v66
	v_mul_f32_e32 v44, -2.0, v55
	v_mul_f32_e32 v45, 0x3e4ccccd, v44
	v_fma_f32 v157, v44, s81, 1.0
	v_pk_mul_f32 v[50:51], v[44:45], v[156:157]
	v_mul_f32_e32 v56, 0x3eaaaaab, v44
	v_sub_f32_e32 v45, 1.0, v51
	v_fma_f32 v159, -v50, v45, 1.0
	v_mov_b32_e32 v45, v56
	v_pk_mul_f32 v[50:51], v[44:45], v[158:159]
	v_sub_f32_e32 v45, 1.0, v51
	v_fma_f32 v45, -v50, v45, 1.0
	v_mul_f32_e32 v44, v44, v45
	v_max_f32_e32 v44, 0, v44
	v_rcp_f32_e32 v42, v42
	v_add_f32_e32 v43, 1.0, v43
	v_cvt_pk_bf16_f32 v41, v58, v41
; DI unsigned pk2(float a, float b) { f32x2 v = {a, b}; bf16v2_t r = __builtin_convertvector(v, bf16v2_t); return __builtin_bit_cast(unsigned, r); }
; DI float sigm(float x) { return 1.f / (1.f + __expf(-x)); }
;     DI void operator()(const Acc& acc, const Unit& u, int wr, int wc, int fr, int fq, const float (&pre)[8]) const {
;     ...
;         for (int n = 0; n < 2; ++n) {
;             const f32x4 br = *(const f32x4*)(brg + f0 + 4 * n), bi = *(const f32x4*)(big + f0 + 4 * n), sp = *(const f32x4*)(sp8t + f0 + 4 * n);
; #pragma unroll
;             for (int ai = 0; ai < 2; ++ai)
; #pragma unroll
;                 for (int m = 0; m < 4; ++m) { const size_t o = (size_t)(row0 + ai * HALF + m * 16) * DM + f0 + 4 * n;
;                     const u32x2 xw = *(const u32x2*)(xc + o);
;                     const float xv[4] = {__uint_as_float(xw.x << 16), __uint_as_float(xw.x & 0xffff0000u), __uint_as_float(xw.y << 16), __uint_as_float(xw.y & 0xffff0000u)};
;                     u32x4 w;
; #pragma unroll
;                     for (int e = 0; e < 4; ++e) { const float r = sigm(acc[ai][0][m][n][e] + br[e]), ig = sigm(acc[ai][1][m][n][e] + bi[e]);
;                         const float la = -sp[e] * r, uu = -2.f * la;
;                         const float om = uu * (1.f - uu * 0.5f * (1.f - uu * (1.f / 3.f) * (1.f - uu * 0.25f * (1.f - uu * 0.2f * (1.f - uu * (1.f / 6.f))))));
;                         w[e] = pk2(la, sqrtf(fmaxf(om, 0.f)) * ig * xv[e]); }
;                     *(u32x4*)(ax + o) = w; __builtin_amdgcn_sched_barrier(0); }
	v_sqrt_f32_e32 v44, v44
	v_add_f32_e32 v45, 1.0, v47
	v_mul_f32_e32 v42, v42, v44
	v_mul_f32_e32 v42, v42, v53
	v_cvt_pk_bf16_f32 v42, v55, v42
	v_rcp_f32_e32 v44, v45
	s_nop 0
	v_mul_f32_e64 v53, v44, -v67
	v_mul_f32_e32 v44, -2.0, v53
	v_mul_f32_e32 v45, 0x3e4ccccd, v44
	v_fma_f32 v157, v44, s81, 1.0
	v_pk_mul_f32 v[46:47], v[44:45], v[156:157]
	v_mul_f32_e32 v54, 0x3eaaaaab, v44
	v_sub_f32_e32 v45, 1.0, v47
	v_fma_f32 v159, -v46, v45, 1.0
	v_mov_b32_e32 v45, v54
	v_pk_mul_f32 v[46:47], v[44:45], v[158:159]
	s_nop 0
	v_sub_f32_e32 v45, 1.0, v47
	v_fma_f32 v45, -v46, v45, 1.0
	v_mul_f32_e32 v44, v44, v45
	v_max_f32_e32 v44, 0, v44
	v_rcp_f32_e32 v43, v43
	v_sqrt_f32_e32 v44, v44
	s_nop 0
	v_mul_f32_e32 v43, v43, v44
	v_mul_f32_e32 v43, v43, v57
	v_cvt_pk_bf16_f32 v43, v53, v43
	v_lshl_add_u64 v[44:45], v[48:49], 2, s[36:37]
	flat_store_dwordx4 v[44:45], v[40:43]
	s_nop 1
	v_lshl_add_u64 v[40:41], v[116:117], 0, v[160:161]
	v_lshl_add_u64 v[42:43], v[40:41], 1, s[16:17]
	flat_load_dwordx2 v[42:43], v[42:43]
	v_add_f32_e32 v36, v36, v72
	v_add_f32_e32 v37, v37, v73
	v_mul_f32_e32 v36, 0xbfb8aa3b, v36
	v_mul_f32_e32 v37, 0xbfb8aa3b, v37
	v_exp_f32_e32 v36, v36
	v_exp_f32_e32 v37, v37
	v_add_f32_e32 v32, v32, v68
	v_mul_f32_e32 v32, 0xbfb8aa3b, v32
	v_add_f32_e32 v36, 1.0, v36
	v_add_f32_e32 v46, 1.0, v37
	v_exp_f32_e32 v32, v32
	s_nop 0
	v_add_f32_e32 v32, 1.0, v32
	v_rcp_f32_e32 v36, v36
	s_nop 0
	v_mul_f32_e64 v48, v36, -v64
	v_mul_f32_e32 v36, -2.0, v48
	v_mul_f32_e32 v37, 0x3e4ccccd, v36
	v_fma_f32 v157, v36, s81, 1.0
	v_pk_mul_f32 v[44:45], v[36:37], v[156:157]
	v_mul_f32_e32 v52, 0x3eaaaaab, v36
	v_sub_f32_e32 v45, 1.0, v45
	v_mov_b32_e32 v37, v52
	v_fma_f32 v159, -v44, v45, 1.0
	v_pk_mul_f32 v[44:45], v[36:37], v[158:159]
	v_sub_f32_e32 v37, 1.0, v45
	v_fma_f32 v37, -v44, v37, 1.0
	v_mul_f32_e32 v36, v36, v37
	v_max_f32_e32 v36, 0, v36
	v_rcp_f32_e32 v32, v32
	v_add_f32_e32 v33, v33, v69
	v_mul_f32_e32 v33, 0xbfb8aa3b, v33
	v_exp_f32_e32 v33, v33
	s_nop 0
	v_add_f32_e32 v33, 1.0, v33
	v_add_f32_e32 v38, v38, v74
	v_mul_f32_e32 v38, 0xbfb8aa3b, v38
	v_exp_f32_e32 v38, v38
	s_waitcnt vmcnt(0) lgkmcnt(0)
	v_and_b32_e32 v44, 0xffff0000, v42
	v_lshlrev_b32_e32 v45, 16, v43
	v_sqrt_f32_e32 v36, v36
	s_nop 0
	v_mul_f32_e32 v32, v32, v36
	v_lshlrev_b32_e32 v36, 16, v42
	v_mul_f32_e32 v32, v32, v36
	v_rcp_f32_e32 v36, v46
	v_and_b32_e32 v49, 0xffff0000, v43
	v_mul_f32_e64 v50, v36, -v65
	v_mul_f32_e32 v36, -2.0, v50
	v_cvt_pk_bf16_f32 v32, v48, v32
	v_mul_f32_e32 v37, 0x3e4ccccd, v36
	v_fma_f32 v157, v36, s81, 1.0
	v_pk_mul_f32 v[42:43], v[36:37], v[156:157]
	v_mul_f32_e32 v51, 0x3eaaaaab, v36
	v_sub_f32_e32 v37, 1.0, v43
	v_fma_f32 v159, -v42, v37, 1.0
	v_mov_b32_e32 v37, v51
	v_pk_mul_f32 v[42:43], v[36:37], v[158:159]
	v_add_f32_e32 v34, v34, v70
	v_sub_f32_e32 v37, 1.0, v43
	v_fma_f32 v37, -v42, v37, 1.0
	v_mul_f32_e32 v36, v36, v37
	v_max_f32_e32 v36, 0, v36
	v_rcp_f32_e32 v33, v33
	v_mul_f32_e32 v34, 0xbfb8aa3b, v34
	v_exp_f32_e32 v34, v34
	v_add_f32_e32 v39, v39, v75
	v_add_f32_e32 v34, 1.0, v34
	v_mul_f32_e32 v39, 0xbfb8aa3b, v39
	v_exp_f32_e32 v39, v39
	v_add_f32_e32 v35, v35, v71
	v_mul_f32_e32 v35, 0xbfb8aa3b, v35
	v_sqrt_f32_e32 v36, v36
	v_add_f32_e32 v37, 1.0, v38
	v_mul_f32_e32 v33, v33, v36
	v_mul_f32_e32 v33, v33, v44
	v_exp_f32_e32 v35, v35
	v_rcp_f32_e32 v36, v37
	s_nop 0
	v_mul_f32_e64 v47, v36, -v66
	v_mul_f32_e32 v36, -2.0, v47
	v_mul_f32_e32 v37, 0x3e4ccccd, v36
	v_fma_f32 v157, v36, s81, 1.0
	v_pk_mul_f32 v[42:43], v[36:37], v[156:157]
	v_mul_f32_e32 v48, 0x3eaaaaab, v36
	v_sub_f32_e32 v37, 1.0, v43
	v_fma_f32 v159, -v42, v37, 1.0
	v_mov_b32_e32 v37, v48
	v_pk_mul_f32 v[42:43], v[36:37], v[158:159]
	v_sub_f32_e32 v37, 1.0, v43
	v_fma_f32 v37, -v42, v37, 1.0
	v_mul_f32_e32 v36, v36, v37
	v_max_f32_e32 v36, 0, v36
	v_rcp_f32_e32 v34, v34
	v_add_f32_e32 v35, 1.0, v35
	v_cvt_pk_bf16_f32 v33, v50, v33
	v_sqrt_f32_e32 v36, v36
	v_add_f32_e32 v37, 1.0, v39
	v_mul_f32_e32 v34, v34, v36
	v_mul_f32_e32 v34, v34, v45
	v_cvt_pk_bf16_f32 v34, v47, v34
	v_rcp_f32_e32 v36, v37
	s_nop 0
	v_mul_f32_e64 v45, v36, -v67
	v_mul_f32_e32 v36, -2.0, v45
	v_mul_f32_e32 v37, 0x3e4ccccd, v36
	v_fma_f32 v157, v36, s81, 1.0
	v_pk_mul_f32 v[38:39], v[36:37], v[156:157]
	v_mul_f32_e32 v46, 0x3eaaaaab, v36
	v_sub_f32_e32 v37, 1.0, v39
	v_fma_f32 v159, -v38, v37, 1.0
	v_mov_b32_e32 v37, v46
	v_pk_mul_f32 v[38:39], v[36:37], v[158:159]
	s_nop 0
	v_sub_f32_e32 v37, 1.0, v39
	v_fma_f32 v37, -v38, v37, 1.0
	v_mul_f32_e32 v36, v36, v37
	v_max_f32_e32 v36, 0, v36
	v_rcp_f32_e32 v35, v35
	v_sqrt_f32_e32 v36, v36
	s_nop 0
	v_mul_f32_e32 v35, v35, v36
	v_mul_f32_e32 v35, v35, v49
	v_cvt_pk_bf16_f32 v35, v45, v35
	v_lshl_add_u64 v[36:37], v[40:41], 2, s[36:37]
	flat_store_dwordx4 v[36:37], v[32:35]
	s_nop 1
	v_lshl_add_u64 v[32:33], v[108:109], 0, v[160:161]
	v_lshl_add_u64 v[34:35], v[32:33], 1, s[16:17]
	flat_load_dwordx2 v[34:35], v[34:35]
	v_add_f32_e32 v28, v28, v72
	v_add_f32_e32 v29, v29, v73
	v_mul_f32_e32 v28, 0xbfb8aa3b, v28
	v_mul_f32_e32 v29, 0xbfb8aa3b, v29
	v_exp_f32_e32 v28, v28
	v_exp_f32_e32 v29, v29
	v_add_f32_e32 v24, v24, v68
	v_mul_f32_e32 v24, 0xbfb8aa3b, v24
	v_add_f32_e32 v28, 1.0, v28
	v_add_f32_e32 v38, 1.0, v29
	v_exp_f32_e32 v24, v24
	s_nop 0
	v_add_f32_e32 v24, 1.0, v24
	v_rcp_f32_e32 v28, v28
	s_nop 0
	v_mul_f32_e64 v40, v28, -v64
	v_mul_f32_e32 v28, -2.0, v40
	v_mul_f32_e32 v29, 0x3e4ccccd, v28
	v_fma_f32 v157, v28, s81, 1.0
	v_pk_mul_f32 v[36:37], v[28:29], v[156:157]
	v_mul_f32_e32 v44, 0x3eaaaaab, v28
	v_sub_f32_e32 v37, 1.0, v37
	v_mov_b32_e32 v29, v44
	v_fma_f32 v159, -v36, v37, 1.0
	v_pk_mul_f32 v[36:37], v[28:29], v[158:159]
	v_sub_f32_e32 v29, 1.0, v37
	v_fma_f32 v29, -v36, v29, 1.0
	v_mul_f32_e32 v28, v28, v29
	v_max_f32_e32 v28, 0, v28
	v_rcp_f32_e32 v24, v24
	v_add_f32_e32 v25, v25, v69
	v_mul_f32_e32 v25, 0xbfb8aa3b, v25
	v_exp_f32_e32 v25, v25
	s_nop 0
	v_add_f32_e32 v25, 1.0, v25
	v_add_f32_e32 v30, v30, v74
	v_mul_f32_e32 v30, 0xbfb8aa3b, v30
	v_exp_f32_e32 v30, v30
	s_waitcnt vmcnt(0) lgkmcnt(0)
; DI unsigned pk2(float a, float b) { f32x2 v = {a, b}; bf16v2_t r = __builtin_convertvector(v, bf16v2_t); return __builtin_bit_cast(unsigned, r); }
; DI float sigm(float x) { return 1.f / (1.f + __expf(-x)); }
;     DI void operator()(const Acc& acc, const Unit& u, int wr, int wc, int fr, int fq, const float (&pre)[8]) const {
;     ...
;         for (int n = 0; n < 2; ++n) {
;             const f32x4 br = *(const f32x4*)(brg + f0 + 4 * n), bi = *(const f32x4*)(big + f0 + 4 * n), sp = *(const f32x4*)(sp8t + f0 + 4 * n);
; #pragma unroll
;             for (int ai = 0; ai < 2; ++ai)
; #pragma unroll
;                 for (int m = 0; m < 4; ++m) { const size_t o = (size_t)(row0 + ai * HALF + m * 16) * DM + f0 + 4 * n;
;                     const u32x2 xw = *(const u32x2*)(xc + o);
;                     const float xv[4] = {__uint_as_float(xw.x << 16), __uint_as_float(xw.x & 0xffff0000u), __uint_as_float(xw.y << 16), __uint_as_float(xw.y & 0xffff0000u)};
;                     u32x4 w;
; #pragma unroll
;                     for (int e = 0; e < 4; ++e) { const float r = sigm(acc[ai][0][m][n][e] + br[e]), ig = sigm(acc[ai][1][m][n][e] + bi[e]);
;                         const float la = -sp[e] * r, uu = -2.f * la;
;                         const float om = uu * (1.f - uu * 0.5f * (1.f - uu * (1.f / 3.f) * (1.f - uu * 0.25f * (1.f - uu * 0.2f * (1.f - uu * (1.f / 6.f))))));
;                         w[e] = pk2(la, sqrtf(fmaxf(om, 0.f)) * ig * xv[e]); }
;                     *(u32x4*)(ax + o) = w; __builtin_amdgcn_sched_barrier(0); }
	v_and_b32_e32 v36, 0xffff0000, v34
	v_lshlrev_b32_e32 v37, 16, v35
	v_sqrt_f32_e32 v28, v28
	s_nop 0
	v_mul_f32_e32 v24, v24, v28
	v_lshlrev_b32_e32 v28, 16, v34
	v_mul_f32_e32 v24, v24, v28
	v_rcp_f32_e32 v28, v38
	v_and_b32_e32 v41, 0xffff0000, v35
	v_mul_f32_e64 v42, v28, -v65
	v_mul_f32_e32 v28, -2.0, v42
	v_cvt_pk_bf16_f32 v24, v40, v24
	v_mul_f32_e32 v29, 0x3e4ccccd, v28
	v_fma_f32 v157, v28, s81, 1.0
	v_pk_mul_f32 v[34:35], v[28:29], v[156:157]
	v_mul_f32_e32 v43, 0x3eaaaaab, v28
	v_sub_f32_e32 v29, 1.0, v35
	v_fma_f32 v159, -v34, v29, 1.0
	v_mov_b32_e32 v29, v43
	v_pk_mul_f32 v[34:35], v[28:29], v[158:159]
	v_add_f32_e32 v26, v26, v70
	v_sub_f32_e32 v29, 1.0, v35
	v_fma_f32 v29, -v34, v29, 1.0
	v_mul_f32_e32 v28, v28, v29
	v_max_f32_e32 v28, 0, v28
	v_rcp_f32_e32 v25, v25
	v_mul_f32_e32 v26, 0xbfb8aa3b, v26
	v_exp_f32_e32 v26, v26
	v_add_f32_e32 v31, v31, v75
	v_add_f32_e32 v26, 1.0, v26
	v_mul_f32_e32 v31, 0xbfb8aa3b, v31
	v_exp_f32_e32 v31, v31
	v_add_f32_e32 v27, v27, v71
	v_mul_f32_e32 v27, 0xbfb8aa3b, v27
	v_sqrt_f32_e32 v28, v28
	v_add_f32_e32 v29, 1.0, v30
	v_mul_f32_e32 v25, v25, v28
	v_mul_f32_e32 v25, v25, v36
	v_exp_f32_e32 v27, v27
	v_rcp_f32_e32 v28, v29
	s_nop 0
	v_mul_f32_e64 v39, v28, -v66
	v_mul_f32_e32 v28, -2.0, v39
	v_mul_f32_e32 v29, 0x3e4ccccd, v28
	v_fma_f32 v157, v28, s81, 1.0
	v_pk_mul_f32 v[34:35], v[28:29], v[156:157]
	v_mul_f32_e32 v40, 0x3eaaaaab, v28
	v_sub_f32_e32 v29, 1.0, v35
	v_fma_f32 v159, -v34, v29, 1.0
	v_mov_b32_e32 v29, v40
	v_pk_mul_f32 v[34:35], v[28:29], v[158:159]
	v_sub_f32_e32 v29, 1.0, v35
	v_fma_f32 v29, -v34, v29, 1.0
	v_mul_f32_e32 v28, v28, v29
	v_max_f32_e32 v28, 0, v28
	v_rcp_f32_e32 v26, v26
	v_add_f32_e32 v27, 1.0, v27
	v_cvt_pk_bf16_f32 v25, v42, v25
	v_sqrt_f32_e32 v28, v28
	v_add_f32_e32 v29, 1.0, v31
	v_mul_f32_e32 v26, v26, v28
	v_mul_f32_e32 v26, v26, v37
	v_cvt_pk_bf16_f32 v26, v39, v26
	v_rcp_f32_e32 v28, v29
	s_nop 0
	v_mul_f32_e64 v37, v28, -v67
	v_mul_f32_e32 v28, -2.0, v37
	v_mul_f32_e32 v29, 0x3e4ccccd, v28
	v_fma_f32 v157, v28, s81, 1.0
	v_pk_mul_f32 v[30:31], v[28:29], v[156:157]
	v_mul_f32_e32 v38, 0x3eaaaaab, v28
	v_sub_f32_e32 v29, 1.0, v31
	v_fma_f32 v159, -v30, v29, 1.0
	v_mov_b32_e32 v29, v38
	v_pk_mul_f32 v[30:31], v[28:29], v[158:159]
	s_nop 0
	v_sub_f32_e32 v29, 1.0, v31
	v_fma_f32 v29, -v30, v29, 1.0
	v_mul_f32_e32 v28, v28, v29
	v_max_f32_e32 v28, 0, v28
	v_rcp_f32_e32 v27, v27
	v_sqrt_f32_e32 v28, v28
	s_nop 0
	v_mul_f32_e32 v27, v27, v28
	v_mul_f32_e32 v27, v27, v41
	v_cvt_pk_bf16_f32 v27, v37, v27
	v_lshl_add_u64 v[28:29], v[32:33], 2, s[36:37]
	flat_store_dwordx4 v[28:29], v[24:27]
	s_nop 1
	v_lshl_add_u64 v[24:25], v[100:101], 0, v[160:161]
	v_lshl_add_u64 v[26:27], v[24:25], 1, s[16:17]
	flat_load_dwordx2 v[26:27], v[26:27]
	v_add_f32_e32 v20, v20, v72
	v_add_f32_e32 v21, v21, v73
	v_mul_f32_e32 v20, 0xbfb8aa3b, v20
	v_mul_f32_e32 v21, 0xbfb8aa3b, v21
	v_exp_f32_e32 v20, v20
	v_exp_f32_e32 v21, v21
	v_add_f32_e32 v16, v16, v68
	v_mul_f32_e32 v16, 0xbfb8aa3b, v16
	v_add_f32_e32 v20, 1.0, v20
	v_add_f32_e32 v30, 1.0, v21
	v_exp_f32_e32 v16, v16
	s_nop 0
	v_add_f32_e32 v16, 1.0, v16
	v_rcp_f32_e32 v20, v20
	s_nop 0
	v_mul_f32_e64 v32, v20, -v64
	v_mul_f32_e32 v20, -2.0, v32
	v_mul_f32_e32 v21, 0x3e4ccccd, v20
	v_fma_f32 v157, v20, s81, 1.0
	v_pk_mul_f32 v[28:29], v[20:21], v[156:157]
	v_mul_f32_e32 v36, 0x3eaaaaab, v20
	v_sub_f32_e32 v29, 1.0, v29
	v_mov_b32_e32 v21, v36
	v_fma_f32 v159, -v28, v29, 1.0
	v_pk_mul_f32 v[28:29], v[20:21], v[158:159]
	v_sub_f32_e32 v21, 1.0, v29
	v_fma_f32 v21, -v28, v21, 1.0
	v_mul_f32_e32 v20, v20, v21
	v_max_f32_e32 v20, 0, v20
	v_rcp_f32_e32 v16, v16
	v_add_f32_e32 v17, v17, v69
	v_mul_f32_e32 v17, 0xbfb8aa3b, v17
	v_exp_f32_e32 v17, v17
	s_nop 0
	v_add_f32_e32 v17, 1.0, v17
	v_add_f32_e32 v22, v22, v74
	v_mul_f32_e32 v22, 0xbfb8aa3b, v22
	v_exp_f32_e32 v22, v22
	s_waitcnt vmcnt(0) lgkmcnt(0)
	v_and_b32_e32 v28, 0xffff0000, v26
	v_lshlrev_b32_e32 v29, 16, v27
	v_sqrt_f32_e32 v20, v20
	s_nop 0
	v_mul_f32_e32 v16, v16, v20
	v_lshlrev_b32_e32 v20, 16, v26
	v_mul_f32_e32 v16, v16, v20
	v_rcp_f32_e32 v20, v30
	v_and_b32_e32 v33, 0xffff0000, v27
	v_mul_f32_e64 v34, v20, -v65
	v_mul_f32_e32 v20, -2.0, v34
	v_cvt_pk_bf16_f32 v16, v32, v16
	v_mul_f32_e32 v21, 0x3e4ccccd, v20
	v_fma_f32 v157, v20, s81, 1.0
	v_pk_mul_f32 v[26:27], v[20:21], v[156:157]
	v_mul_f32_e32 v35, 0x3eaaaaab, v20
	v_sub_f32_e32 v21, 1.0, v27
	v_fma_f32 v159, -v26, v21, 1.0
	v_mov_b32_e32 v21, v35
	v_pk_mul_f32 v[26:27], v[20:21], v[158:159]
	v_add_f32_e32 v18, v18, v70
	v_sub_f32_e32 v21, 1.0, v27
	v_fma_f32 v21, -v26, v21, 1.0
	v_mul_f32_e32 v20, v20, v21
	v_max_f32_e32 v20, 0, v20
	v_rcp_f32_e32 v17, v17
	v_mul_f32_e32 v18, 0xbfb8aa3b, v18
	v_exp_f32_e32 v18, v18
	v_add_f32_e32 v23, v23, v75
	v_add_f32_e32 v18, 1.0, v18
	v_mul_f32_e32 v23, 0xbfb8aa3b, v23
	v_exp_f32_e32 v23, v23
	v_add_f32_e32 v19, v19, v71
	v_mul_f32_e32 v19, 0xbfb8aa3b, v19
	v_sqrt_f32_e32 v20, v20
	v_add_f32_e32 v21, 1.0, v22
	v_mul_f32_e32 v17, v17, v20
	v_mul_f32_e32 v17, v17, v28
	v_exp_f32_e32 v19, v19
	v_rcp_f32_e32 v20, v21
	s_nop 0
	v_mul_f32_e64 v31, v20, -v66
	v_mul_f32_e32 v20, -2.0, v31
	v_mul_f32_e32 v21, 0x3e4ccccd, v20
	v_fma_f32 v157, v20, s81, 1.0
	v_pk_mul_f32 v[26:27], v[20:21], v[156:157]
	v_mul_f32_e32 v32, 0x3eaaaaab, v20
	v_sub_f32_e32 v21, 1.0, v27
	v_fma_f32 v159, -v26, v21, 1.0
	v_mov_b32_e32 v21, v32
	v_pk_mul_f32 v[26:27], v[20:21], v[158:159]
	v_sub_f32_e32 v21, 1.0, v27
	v_fma_f32 v21, -v26, v21, 1.0
	v_mul_f32_e32 v20, v20, v21
	v_max_f32_e32 v20, 0, v20
	v_rcp_f32_e32 v18, v18
	v_add_f32_e32 v19, 1.0, v19
	v_cvt_pk_bf16_f32 v17, v34, v17
; DI unsigned pk2(float a, float b) { f32x2 v = {a, b}; bf16v2_t r = __builtin_convertvector(v, bf16v2_t); return __builtin_bit_cast(unsigned, r); }
; DI float sigm(float x) { return 1.f / (1.f + __expf(-x)); }
;     DI void operator()(const Acc& acc, const Unit& u, int wr, int wc, int fr, int fq, const float (&pre)[8]) const {
;     ...
;                     for (int e = 0; e < 4; ++e) { const float r = sigm(acc[ai][0][m][n][e] + br[e]), ig = sigm(acc[ai][1][m][n][e] + bi[e]);
;                         const float la = -sp[e] * r, uu = -2.f * la;
;                         const float om = uu * (1.f - uu * 0.5f * (1.f - uu * (1.f / 3.f) * (1.f - uu * 0.25f * (1.f - uu * 0.2f * (1.f - uu * (1.f / 6.f))))));
;                         w[e] = pk2(la, sqrtf(fmaxf(om, 0.f)) * ig * xv[e]); }
;                     *(u32x4*)(ax + o) = w; __builtin_amdgcn_sched_barrier(0); }
	v_sqrt_f32_e32 v20, v20
	v_add_f32_e32 v21, 1.0, v23
	v_mul_f32_e32 v18, v18, v20
	v_mul_f32_e32 v18, v18, v29
	v_cvt_pk_bf16_f32 v18, v31, v18
	v_rcp_f32_e32 v20, v21
	s_nop 0
	v_mul_f32_e64 v29, v20, -v67
	v_mul_f32_e32 v20, -2.0, v29
	v_mul_f32_e32 v21, 0x3e4ccccd, v20
	v_fma_f32 v157, v20, s81, 1.0
	v_pk_mul_f32 v[22:23], v[20:21], v[156:157]
	v_mul_f32_e32 v30, 0x3eaaaaab, v20
	v_sub_f32_e32 v21, 1.0, v23
	v_fma_f32 v159, -v22, v21, 1.0
	v_mov_b32_e32 v21, v30
	v_pk_mul_f32 v[22:23], v[20:21], v[158:159]
	s_nop 0
	v_sub_f32_e32 v21, 1.0, v23
	v_fma_f32 v21, -v22, v21, 1.0
	v_mul_f32_e32 v20, v20, v21
	v_max_f32_e32 v20, 0, v20
	v_rcp_f32_e32 v19, v19
	v_sqrt_f32_e32 v20, v20
	s_nop 0
	v_mul_f32_e32 v19, v19, v20
	v_mul_f32_e32 v19, v19, v33
	v_cvt_pk_bf16_f32 v19, v29, v19
	v_lshl_add_u64 v[20:21], v[24:25], 2, s[36:37]
	flat_store_dwordx4 v[20:21], v[16:19]
	s_nop 1
	v_lshl_add_u64 v[16:17], v[80:81], 0, v[160:161]
	v_lshl_add_u64 v[18:19], v[16:17], 1, s[16:17]
	flat_load_dwordx2 v[18:19], v[18:19]
	v_add_f32_e32 v12, v12, v72
	v_add_f32_e32 v13, v13, v73
	v_mul_f32_e32 v12, 0xbfb8aa3b, v12
	v_mul_f32_e32 v13, 0xbfb8aa3b, v13
	v_exp_f32_e32 v12, v12
	v_exp_f32_e32 v13, v13
	v_add_f32_e32 v8, v8, v68
	v_mul_f32_e32 v8, 0xbfb8aa3b, v8
	v_add_f32_e32 v12, 1.0, v12
	v_add_f32_e32 v22, 1.0, v13
	v_exp_f32_e32 v8, v8
	s_nop 0
	v_add_f32_e32 v8, 1.0, v8
	v_rcp_f32_e32 v12, v12
	s_nop 0
	v_mul_f32_e64 v24, v12, -v64
	v_mul_f32_e32 v12, -2.0, v24
	v_mul_f32_e32 v13, 0x3e4ccccd, v12
	v_fma_f32 v157, v12, s81, 1.0
	v_pk_mul_f32 v[20:21], v[12:13], v[156:157]
	v_mul_f32_e32 v28, 0x3eaaaaab, v12
	v_sub_f32_e32 v21, 1.0, v21
	v_mov_b32_e32 v13, v28
	v_fma_f32 v159, -v20, v21, 1.0
	v_pk_mul_f32 v[20:21], v[12:13], v[158:159]
	v_sub_f32_e32 v13, 1.0, v21
	v_fma_f32 v13, -v20, v13, 1.0
	v_mul_f32_e32 v12, v12, v13
	v_max_f32_e32 v12, 0, v12
	v_rcp_f32_e32 v8, v8
	v_add_f32_e32 v9, v9, v69
	v_mul_f32_e32 v9, 0xbfb8aa3b, v9
	v_exp_f32_e32 v9, v9
	s_nop 0
	v_add_f32_e32 v9, 1.0, v9
	v_add_f32_e32 v14, v14, v74
	v_mul_f32_e32 v14, 0xbfb8aa3b, v14
	v_exp_f32_e32 v14, v14
	s_waitcnt vmcnt(0) lgkmcnt(0)
	v_and_b32_e32 v20, 0xffff0000, v18
	v_lshlrev_b32_e32 v21, 16, v19
	v_sqrt_f32_e32 v12, v12
	s_nop 0
	v_mul_f32_e32 v8, v8, v12
	v_lshlrev_b32_e32 v12, 16, v18
	v_mul_f32_e32 v8, v8, v12
	v_rcp_f32_e32 v12, v22
	v_and_b32_e32 v25, 0xffff0000, v19
	v_mul_f32_e64 v26, v12, -v65
	v_mul_f32_e32 v12, -2.0, v26
	v_cvt_pk_bf16_f32 v8, v24, v8
	v_mul_f32_e32 v13, 0x3e4ccccd, v12
	v_fma_f32 v157, v12, s81, 1.0
	v_pk_mul_f32 v[18:19], v[12:13], v[156:157]
	v_mul_f32_e32 v27, 0x3eaaaaab, v12
	v_sub_f32_e32 v13, 1.0, v19
	v_fma_f32 v159, -v18, v13, 1.0
	v_mov_b32_e32 v13, v27
	v_pk_mul_f32 v[18:19], v[12:13], v[158:159]
	v_add_f32_e32 v10, v10, v70
	v_sub_f32_e32 v13, 1.0, v19
	v_fma_f32 v13, -v18, v13, 1.0
	v_mul_f32_e32 v12, v12, v13
	v_max_f32_e32 v12, 0, v12
	v_rcp_f32_e32 v9, v9
	v_mul_f32_e32 v10, 0xbfb8aa3b, v10
	v_exp_f32_e32 v10, v10
	v_add_f32_e32 v15, v15, v75
	v_add_f32_e32 v10, 1.0, v10
	v_mul_f32_e32 v15, 0xbfb8aa3b, v15
	v_exp_f32_e32 v15, v15
	v_add_f32_e32 v11, v11, v71
	v_mul_f32_e32 v11, 0xbfb8aa3b, v11
	v_sqrt_f32_e32 v12, v12
	v_add_f32_e32 v13, 1.0, v14
	v_mul_f32_e32 v9, v9, v12
	v_mul_f32_e32 v9, v9, v20
	v_exp_f32_e32 v11, v11
	v_rcp_f32_e32 v12, v13
	s_nop 0
	v_mul_f32_e64 v23, v12, -v66
	v_mul_f32_e32 v12, -2.0, v23
	v_mul_f32_e32 v13, 0x3e4ccccd, v12
	v_fma_f32 v157, v12, s81, 1.0
	v_pk_mul_f32 v[18:19], v[12:13], v[156:157]
	v_mul_f32_e32 v24, 0x3eaaaaab, v12
	v_sub_f32_e32 v13, 1.0, v19
	v_fma_f32 v159, -v18, v13, 1.0
	v_mov_b32_e32 v13, v24
	v_pk_mul_f32 v[18:19], v[12:13], v[158:159]
	v_sub_f32_e32 v13, 1.0, v19
	v_fma_f32 v13, -v18, v13, 1.0
	v_mul_f32_e32 v12, v12, v13
	v_max_f32_e32 v12, 0, v12
	v_rcp_f32_e32 v10, v10
	v_add_f32_e32 v11, 1.0, v11
	v_cvt_pk_bf16_f32 v9, v26, v9
	v_sqrt_f32_e32 v12, v12
	v_add_f32_e32 v13, 1.0, v15
	v_mul_f32_e32 v10, v10, v12
	v_mul_f32_e32 v10, v10, v21
	v_cvt_pk_bf16_f32 v10, v23, v10
	v_rcp_f32_e32 v12, v13
	s_nop 0
	v_mul_f32_e64 v21, v12, -v67
	v_mul_f32_e32 v12, -2.0, v21
	v_mul_f32_e32 v13, 0x3e4ccccd, v12
	v_fma_f32 v157, v12, s81, 1.0
	v_pk_mul_f32 v[14:15], v[12:13], v[156:157]
	v_mul_f32_e32 v22, 0x3eaaaaab, v12
	v_sub_f32_e32 v13, 1.0, v15
	v_fma_f32 v159, -v14, v13, 1.0
	v_mov_b32_e32 v13, v22
	v_pk_mul_f32 v[14:15], v[12:13], v[158:159]
	s_nop 0
	v_sub_f32_e32 v13, 1.0, v15
	v_fma_f32 v13, -v14, v13, 1.0
	v_mul_f32_e32 v12, v12, v13
	v_max_f32_e32 v12, 0, v12
	v_rcp_f32_e32 v11, v11
	v_sqrt_f32_e32 v12, v12
	s_nop 0
	v_mul_f32_e32 v11, v11, v12
	v_mul_f32_e32 v11, v11, v25
	v_cvt_pk_bf16_f32 v11, v21, v11
	v_lshl_add_u64 v[12:13], v[16:17], 2, s[36:37]
	flat_store_dwordx4 v[12:13], v[8:11]
	s_nop 1
	v_lshl_add_u64 v[8:9], v[76:77], 0, v[160:161]
	v_lshl_add_u64 v[10:11], v[8:9], 1, s[16:17]
	flat_load_dwordx2 v[10:11], v[10:11]
	v_add_f32_e32 v4, v4, v72
	v_add_f32_e32 v5, v5, v73
	v_mul_f32_e32 v4, 0xbfb8aa3b, v4
	v_mul_f32_e32 v5, 0xbfb8aa3b, v5
	v_exp_f32_e32 v4, v4
	v_exp_f32_e32 v5, v5
	v_add_f32_e32 v0, v0, v68
	v_mul_f32_e32 v0, 0xbfb8aa3b, v0
	v_add_f32_e32 v4, 1.0, v4
	v_add_f32_e32 v14, 1.0, v5
	v_exp_f32_e32 v0, v0
	s_nop 0
	v_add_f32_e32 v0, 1.0, v0
	v_rcp_f32_e32 v4, v4
	s_nop 0
	v_mul_f32_e64 v16, v4, -v64
	v_mul_f32_e32 v4, -2.0, v16
	v_mul_f32_e32 v5, 0x3e4ccccd, v4
	v_fma_f32 v157, v4, s81, 1.0
	v_pk_mul_f32 v[12:13], v[4:5], v[156:157]
	v_mul_f32_e32 v20, 0x3eaaaaab, v4
	v_sub_f32_e32 v13, 1.0, v13
	v_mov_b32_e32 v5, v20
	v_fma_f32 v159, -v12, v13, 1.0
	v_pk_mul_f32 v[12:13], v[4:5], v[158:159]
	v_sub_f32_e32 v5, 1.0, v13
	v_fma_f32 v5, -v12, v5, 1.0
	v_mul_f32_e32 v4, v4, v5
	v_max_f32_e32 v4, 0, v4
	v_rcp_f32_e32 v0, v0
	v_add_f32_e32 v1, v1, v69
	v_mul_f32_e32 v1, 0xbfb8aa3b, v1
	v_exp_f32_e32 v1, v1
	s_nop 0
	v_add_f32_e32 v1, 1.0, v1
	v_add_f32_e32 v6, v6, v74
	v_mul_f32_e32 v6, 0xbfb8aa3b, v6
	v_exp_f32_e32 v6, v6
	s_waitcnt vmcnt(0) lgkmcnt(0)
; DI unsigned pk2(float a, float b) { f32x2 v = {a, b}; bf16v2_t r = __builtin_convertvector(v, bf16v2_t); return __builtin_bit_cast(unsigned, r); }
; DI float sigm(float x) { return 1.f / (1.f + __expf(-x)); }
;     DI void operator()(const Acc& acc, const Unit& u, int wr, int wc, int fr, int fq, const float (&pre)[8]) const {
;     ...
;                     for (int e = 0; e < 4; ++e) { const float r = sigm(acc[ai][0][m][n][e] + br[e]), ig = sigm(acc[ai][1][m][n][e] + bi[e]);
;                         const float la = -sp[e] * r, uu = -2.f * la;
;                         const float om = uu * (1.f - uu * 0.5f * (1.f - uu * (1.f / 3.f) * (1.f - uu * 0.25f * (1.f - uu * 0.2f * (1.f - uu * (1.f / 6.f))))));
;                         w[e] = pk2(la, sqrtf(fmaxf(om, 0.f)) * ig * xv[e]); }
;                     *(u32x4*)(ax + o) = w; __builtin_amdgcn_sched_barrier(0); }
	v_and_b32_e32 v12, 0xffff0000, v10
	v_lshlrev_b32_e32 v13, 16, v11
	v_sqrt_f32_e32 v4, v4
	s_nop 0
	v_mul_f32_e32 v0, v0, v4
	v_lshlrev_b32_e32 v4, 16, v10
	v_mul_f32_e32 v0, v0, v4
	v_rcp_f32_e32 v4, v14
	v_and_b32_e32 v17, 0xffff0000, v11
	v_mul_f32_e64 v18, v4, -v65
	v_mul_f32_e32 v4, -2.0, v18
	v_cvt_pk_bf16_f32 v0, v16, v0
	v_mul_f32_e32 v5, 0x3e4ccccd, v4
	v_fma_f32 v157, v4, s81, 1.0
	v_pk_mul_f32 v[10:11], v[4:5], v[156:157]
	v_mul_f32_e32 v19, 0x3eaaaaab, v4
	v_sub_f32_e32 v5, 1.0, v11
	v_fma_f32 v159, -v10, v5, 1.0
	v_mov_b32_e32 v5, v19
	v_pk_mul_f32 v[10:11], v[4:5], v[158:159]
	v_add_f32_e32 v2, v2, v70
	v_sub_f32_e32 v5, 1.0, v11
	v_fma_f32 v5, -v10, v5, 1.0
	v_mul_f32_e32 v4, v4, v5
	v_max_f32_e32 v4, 0, v4
	v_rcp_f32_e32 v1, v1
	v_mul_f32_e32 v2, 0xbfb8aa3b, v2
	v_exp_f32_e32 v2, v2
	v_add_f32_e32 v7, v7, v75
	v_add_f32_e32 v2, 1.0, v2
	v_mul_f32_e32 v7, 0xbfb8aa3b, v7
	v_exp_f32_e32 v7, v7
	v_add_f32_e32 v3, v3, v71
	v_mul_f32_e32 v3, 0xbfb8aa3b, v3
	v_sqrt_f32_e32 v4, v4
	v_add_f32_e32 v5, 1.0, v6
	v_mul_f32_e32 v1, v1, v4
	v_mul_f32_e32 v1, v1, v12
	v_exp_f32_e32 v3, v3
	v_rcp_f32_e32 v4, v5
	s_nop 0
	v_mul_f32_e64 v15, v4, -v66
	v_mul_f32_e32 v4, -2.0, v15
	v_mul_f32_e32 v5, 0x3e4ccccd, v4
	v_fma_f32 v157, v4, s81, 1.0
	v_pk_mul_f32 v[10:11], v[4:5], v[156:157]
	v_mul_f32_e32 v16, 0x3eaaaaab, v4
	v_sub_f32_e32 v5, 1.0, v11
	v_fma_f32 v159, -v10, v5, 1.0
	v_mov_b32_e32 v5, v16
	v_pk_mul_f32 v[10:11], v[4:5], v[158:159]
	v_sub_f32_e32 v5, 1.0, v11
	v_fma_f32 v5, -v10, v5, 1.0
	v_mul_f32_e32 v4, v4, v5
	v_max_f32_e32 v4, 0, v4
	v_rcp_f32_e32 v2, v2
	v_add_f32_e32 v3, 1.0, v3
	v_cvt_pk_bf16_f32 v1, v18, v1
	v_sqrt_f32_e32 v4, v4
	v_add_f32_e32 v5, 1.0, v7
	v_mul_f32_e32 v2, v2, v4
	v_mul_f32_e32 v2, v2, v13
	v_cvt_pk_bf16_f32 v2, v15, v2
	v_rcp_f32_e32 v4, v5
	s_nop 0
	v_mul_f32_e64 v13, v4, -v67
	v_mul_f32_e32 v4, -2.0, v13
	v_mul_f32_e32 v5, 0x3e4ccccd, v4
	v_fma_f32 v157, v4, s81, 1.0
	v_pk_mul_f32 v[6:7], v[4:5], v[156:157]
	v_mul_f32_e32 v14, 0x3eaaaaab, v4
	v_sub_f32_e32 v5, 1.0, v7
	v_fma_f32 v159, -v6, v5, 1.0
	v_mov_b32_e32 v5, v14
	v_pk_mul_f32 v[6:7], v[4:5], v[158:159]
	s_nop 0
	v_sub_f32_e32 v5, 1.0, v7
	v_fma_f32 v5, -v6, v5, 1.0
	v_mul_f32_e32 v4, v4, v5
	v_max_f32_e32 v4, 0, v4
	v_rcp_f32_e32 v3, v3
	v_sqrt_f32_e32 v4, v4
	s_nop 0
	v_mul_f32_e32 v3, v3, v4
	v_mul_f32_e32 v3, v3, v17
	v_cvt_pk_bf16_f32 v3, v13, v3
	v_lshl_add_u64 v[4:5], v[8:9], 2, s[36:37]
	flat_store_dwordx4 v[4:5], v[0:3]
	s_and_b64 vcc, exec, s[8:9]
	s_mov_b32 s84, s83
	s_mov_b32 s12, s50
	s_mov_b64 s[14:15], s[58:59]
	s_mov_b64 s[60:61], s[56:57]
	s_cbranch_vccnz .LBB0_954
